# prep phase: 4-byte weight loads of the transpose items without nt (on top of default-policy 8-byte E-phase loads)
# baseline (speedup 1.0000x reference)
; #define LAS __attribute__((address_space(3)))
; #define GAS __attribute__((address_space(1)))
; DI void transpose_item(const GAS float* W, int K, int N, GAS bf16* WT, int vrow0, int scol0, int k0, LAS float* scr, int lane) {
;     float wv[32];
; #pragma unroll
;     for (int i = 0; i < 32; ++i) wv[i] = __builtin_nontemporal_load(W + (size_t)(k0 + 2 * i + (lane >> 5)) * N + scol0 + (lane & 31));
; DI void phase_prep(const Ctx& C) {
;     ...
;             { const int kb = it / 32, nb = it % 32; transpose_item(INP(I_ODWOUT), 1024, 1024, WSP(bf16, WS_WODOUT), 32 * nb, 32 * nb, 64 * kb, scr, lane); continue; }
.LBB0_38:
	s_andn2_b64 vcc, exec, s[0:1]
	s_cbranch_vccnz .LBB0_59
	s_cmpk_gt_u32 s26, 0x307f
	s_mov_b64 s[0:1], -1
	s_cbranch_scc0 .LBB0_57
	s_cmpk_gt_u32 s26, 0x467f
	s_cbranch_scc0 .LBB0_54
	s_cmpk_gt_u32 s26, 0x487f
	s_cbranch_scc0 .LBB0_51
	s_cmpk_gt_u32 s26, 0x4a7f
	s_cbranch_scc0 .LBB0_48
	s_cmpk_gt_u32 s26, 0x4eff
	s_cbranch_scc0 .LBB0_45
	s_lshl_b32 s0, s26, 5
	s_and_b32 s2, s0, 0x3e0
	s_lshl_b32 s0, s26, 1
	s_and_b32 s0, s0, 0xffc0
	s_add_i32 s0, s0, 0xffff6200
	v_or_b32_e32 v68, s0, v101
	s_lshl_b32 s6, s2, 2
	v_or_b32_e32 v6, 2, v68
	v_mov_b32_e32 v7, v69
	v_or_b32_e32 v8, 4, v68
	v_mov_b32_e32 v9, v69
	v_or_b32_e32 v10, 6, v68
	v_mov_b32_e32 v11, v69
	v_or_b32_e32 v12, 8, v68
	v_mov_b32_e32 v13, v69
	v_or_b32_e32 v14, 10, v68
	v_mov_b32_e32 v15, v69
	v_or_b32_e32 v16, 12, v68
	v_mov_b32_e32 v17, v69
	v_lshl_add_u64 v[2:3], v[74:75], 0, s[6:7]
	v_lshlrev_b64 v[4:5], 12, v[68:69]
	v_lshlrev_b64 v[6:7], 12, v[6:7]
	v_lshlrev_b64 v[8:9], 12, v[8:9]
	v_lshlrev_b64 v[10:11], 12, v[10:11]
	v_lshlrev_b64 v[12:13], 12, v[12:13]
	v_lshlrev_b64 v[14:15], 12, v[14:15]
	v_lshlrev_b64 v[16:17], 12, v[16:17]
	v_or_b32_e32 v18, 14, v68
	v_mov_b32_e32 v19, v69
	v_lshl_add_u64 v[4:5], v[2:3], 0, v[4:5]
	v_lshl_add_u64 v[6:7], v[2:3], 0, v[6:7]
	v_lshl_add_u64 v[8:9], v[2:3], 0, v[8:9]
	v_lshl_add_u64 v[10:11], v[2:3], 0, v[10:11]
	v_lshl_add_u64 v[12:13], v[2:3], 0, v[12:13]
	v_lshl_add_u64 v[14:15], v[2:3], 0, v[14:15]
	v_lshl_add_u64 v[16:17], v[2:3], 0, v[16:17]
	v_lshlrev_b64 v[18:19], 12, v[18:19]
	v_lshl_add_u64 v[18:19], v[2:3], 0, v[18:19]
	global_load_dword v20, v[4:5], off
	global_load_dword v21, v[6:7], off
	global_load_dword v22, v[8:9], off
	global_load_dword v23, v[10:11], off
	global_load_dword v24, v[12:13], off
	global_load_dword v25, v[14:15], off
	global_load_dword v26, v[16:17], off
	global_load_dword v27, v[18:19], off
	v_or_b32_e32 v4, 16, v68
	v_mov_b32_e32 v5, v69
	v_or_b32_e32 v6, 18, v68
	v_mov_b32_e32 v7, v69
	v_or_b32_e32 v8, 20, v68
	v_mov_b32_e32 v9, v69
	v_or_b32_e32 v10, 22, v68
	v_mov_b32_e32 v11, v69
	v_or_b32_e32 v12, 24, v68
	v_mov_b32_e32 v13, v69
	v_or_b32_e32 v14, 26, v68
	v_mov_b32_e32 v15, v69
	v_or_b32_e32 v16, 28, v68
	v_mov_b32_e32 v17, v69
	v_lshlrev_b64 v[4:5], 12, v[4:5]
	v_lshlrev_b64 v[6:7], 12, v[6:7]
	v_lshlrev_b64 v[8:9], 12, v[8:9]
	v_lshlrev_b64 v[10:11], 12, v[10:11]
	v_lshlrev_b64 v[12:13], 12, v[12:13]
	v_lshlrev_b64 v[14:15], 12, v[14:15]
	v_lshlrev_b64 v[16:17], 12, v[16:17]
	v_or_b32_e32 v18, 30, v68
	v_mov_b32_e32 v19, v69
	v_lshl_add_u64 v[4:5], v[2:3], 0, v[4:5]
	v_lshl_add_u64 v[6:7], v[2:3], 0, v[6:7]
	v_lshl_add_u64 v[8:9], v[2:3], 0, v[8:9]
	v_lshl_add_u64 v[10:11], v[2:3], 0, v[10:11]
	v_lshl_add_u64 v[12:13], v[2:3], 0, v[12:13]
	v_lshl_add_u64 v[14:15], v[2:3], 0, v[14:15]
	v_lshl_add_u64 v[16:17], v[2:3], 0, v[16:17]
	v_lshlrev_b64 v[18:19], 12, v[18:19]
	v_lshl_add_u64 v[18:19], v[2:3], 0, v[18:19]
	global_load_dword v28, v[4:5], off
	global_load_dword v29, v[6:7], off
	global_load_dword v30, v[8:9], off
	global_load_dword v31, v[10:11], off
	global_load_dword v32, v[12:13], off
	global_load_dword v33, v[14:15], off
	global_load_dword v34, v[16:17], off
	global_load_dword v35, v[18:19], off
	v_or_b32_e32 v4, 32, v68
	v_mov_b32_e32 v5, v69
	v_or_b32_e32 v6, 34, v68
	v_mov_b32_e32 v7, v69
	v_or_b32_e32 v8, 36, v68
	v_mov_b32_e32 v9, v69
	v_or_b32_e32 v10, 38, v68
	v_mov_b32_e32 v11, v69
	v_or_b32_e32 v12, 40, v68
	v_mov_b32_e32 v13, v69
	v_or_b32_e32 v14, 42, v68
	v_mov_b32_e32 v15, v69
	v_or_b32_e32 v16, 44, v68
	v_mov_b32_e32 v17, v69
	v_lshlrev_b64 v[4:5], 12, v[4:5]
	v_lshlrev_b64 v[6:7], 12, v[6:7]
	v_lshlrev_b64 v[8:9], 12, v[8:9]
	v_lshlrev_b64 v[10:11], 12, v[10:11]
	v_lshlrev_b64 v[12:13], 12, v[12:13]
	v_lshlrev_b64 v[14:15], 12, v[14:15]
	v_lshlrev_b64 v[16:17], 12, v[16:17]
	v_or_b32_e32 v18, 46, v68
	v_mov_b32_e32 v19, v69
	v_lshl_add_u64 v[4:5], v[2:3], 0, v[4:5]
	v_lshl_add_u64 v[6:7], v[2:3], 0, v[6:7]
	v_lshl_add_u64 v[8:9], v[2:3], 0, v[8:9]
	v_lshl_add_u64 v[10:11], v[2:3], 0, v[10:11]
	v_lshl_add_u64 v[12:13], v[2:3], 0, v[12:13]
	v_lshl_add_u64 v[14:15], v[2:3], 0, v[14:15]
	v_lshl_add_u64 v[16:17], v[2:3], 0, v[16:17]
	v_lshlrev_b64 v[18:19], 12, v[18:19]
	v_lshl_add_u64 v[18:19], v[2:3], 0, v[18:19]
	global_load_dword v36, v[4:5], off
	global_load_dword v37, v[6:7], off
	global_load_dword v38, v[8:9], off
	global_load_dword v39, v[10:11], off
	global_load_dword v40, v[12:13], off
	global_load_dword v41, v[14:15], off
	global_load_dword v42, v[16:17], off
	global_load_dword v43, v[18:19], off
	v_or_b32_e32 v4, 48, v68
	v_mov_b32_e32 v5, v69
	v_or_b32_e32 v6, 50, v68
	v_mov_b32_e32 v7, v69
	v_or_b32_e32 v8, 52, v68
	v_mov_b32_e32 v9, v69
	v_or_b32_e32 v10, 54, v68
	v_mov_b32_e32 v11, v69
	v_or_b32_e32 v12, 56, v68
	v_mov_b32_e32 v13, v69
	v_or_b32_e32 v14, 58, v68
	v_mov_b32_e32 v15, v69
	v_or_b32_e32 v16, 60, v68
	v_mov_b32_e32 v17, v69
	v_or_b32_e32 v68, 62, v68
	v_lshlrev_b64 v[4:5], 12, v[4:5]
	v_lshlrev_b64 v[6:7], 12, v[6:7]
	v_lshlrev_b64 v[8:9], 12, v[8:9]
	v_lshlrev_b64 v[10:11], 12, v[10:11]
	v_lshlrev_b64 v[12:13], 12, v[12:13]
	v_lshlrev_b64 v[14:15], 12, v[14:15]
	v_lshlrev_b64 v[16:17], 12, v[16:17]
	v_lshlrev_b64 v[18:19], 12, v[68:69]
	v_lshl_add_u64 v[4:5], v[2:3], 0, v[4:5]
	v_lshl_add_u64 v[6:7], v[2:3], 0, v[6:7]
	v_lshl_add_u64 v[8:9], v[2:3], 0, v[8:9]
	v_lshl_add_u64 v[10:11], v[2:3], 0, v[10:11]
	v_lshl_add_u64 v[12:13], v[2:3], 0, v[12:13]
	v_lshl_add_u64 v[14:15], v[2:3], 0, v[14:15]
	v_lshl_add_u64 v[16:17], v[2:3], 0, v[16:17]
	v_lshl_add_u64 v[2:3], v[2:3], 0, v[18:19]
	global_load_dword v4, v[4:5], off
	s_nop 0
	global_load_dword v5, v[6:7], off
	s_nop 0
	global_load_dword v6, v[8:9], off
	global_load_dword v7, v[10:11], off
	s_nop 0
	global_load_dword v8, v[12:13], off
	global_load_dword v9, v[14:15], off
	global_load_dword v10, v[16:17], off
	s_nop 0
	global_load_dword v2, v[2:3], off
	v_add_u32_e32 v3, 0x400, v102
	s_waitcnt vmcnt(30)
; #define LAS __attribute__((address_space(3)))
; #define GAS __attribute__((address_space(1)))
; DI unsigned pk2(float lo, float hi) { f32x2_t v = {lo, hi}; bf16x2_t b = __builtin_convertvector(v, bf16x2_t); return __builtin_bit_cast(unsigned, b); }
; DI void transpose_item(const GAS float* W, int K, int N, GAS bf16* WT, int vrow0, int scol0, int k0, LAS float* scr, int lane) {
;     ...
; #pragma unroll
;     for (int i = 0; i < 32; ++i) scr[(2 * i + (lane >> 5)) * 33 + (lane & 31)] = wv[i];
;     asm volatile("s_waitcnt lgkmcnt(0)" ::: "memory");
;     const int c = lane & 7;
; #pragma unroll
;     for (int j = 0; j < 4; ++j) { const int n = (lane >> 3) + 8 * j; const LAS float* s = scr + (8 * c) * 33 + n;
;         u32x4 o; o.x = pk2(s[0 * 33], s[1 * 33]); o.y = pk2(s[2 * 33], s[3 * 33]); o.z = pk2(s[4 * 33], s[5 * 33]); o.w = pk2(s[6 * 33], s[7 * 33]);
;         *(GAS u32x4*)(WT + (size_t)(vrow0 + n) * K + k0 + 8 * c) = o; }
; DI void phase_prep(const Ctx& C) {
;     ...
;             if (it < T_ODI) { const int kb = it / 72, nb = it % 72; transpose_item(INP(I_ODWIN), 1024, 2304, WSP(bf16, WS_WODIN), 32 * nb, 32 * nb, 64 * kb, scr, lane); continue; }
	ds_write2_b32 v102, v20, v21 offset1:66
	s_waitcnt vmcnt(28)
	ds_write2_b32 v102, v22, v23 offset0:132 offset1:198
	s_waitcnt vmcnt(26)
	ds_write2_b32 v3, v24, v25 offset0:8 offset1:74
	s_waitcnt vmcnt(24)
	ds_write2_b32 v3, v26, v27 offset0:140 offset1:206
	v_add_u32_e32 v3, 0x800, v102
	s_waitcnt vmcnt(22)
	ds_write2_b32 v3, v28, v29 offset0:16 offset1:82
	s_waitcnt vmcnt(20)
	ds_write2_b32 v3, v30, v31 offset0:148 offset1:214
	v_add_u32_e32 v3, 0xc00, v102
	s_waitcnt vmcnt(18)
	ds_write2_b32 v3, v32, v33 offset0:24 offset1:90
	s_waitcnt vmcnt(16)
	ds_write2_b32 v3, v34, v35 offset0:156 offset1:222
	v_add_u32_e32 v3, 0x1000, v102
	s_waitcnt vmcnt(14)
	ds_write2_b32 v3, v36, v37 offset0:32 offset1:98
	s_waitcnt vmcnt(12)
	ds_write2_b32 v3, v38, v39 offset0:164 offset1:230
	v_add_u32_e32 v3, 0x1400, v102
	s_waitcnt vmcnt(10)
	ds_write2_b32 v3, v40, v41 offset0:40 offset1:106
	s_waitcnt vmcnt(8)
	ds_write2_b32 v3, v42, v43 offset0:172 offset1:238
	v_add_u32_e32 v3, 0x1800, v102
	s_waitcnt vmcnt(6)
	ds_write2_b32 v3, v4, v5 offset0:48 offset1:114
	s_waitcnt vmcnt(4)
	ds_write2_b32 v3, v6, v7 offset0:180 offset1:246
	v_add_u32_e32 v3, 0x1c00, v102
	s_waitcnt vmcnt(2)
	ds_write2_b32 v3, v8, v9 offset0:56 offset1:122
	s_waitcnt vmcnt(0)
	ds_write2_b32 v3, v10, v2 offset0:188 offset1:254
	s_waitcnt lgkmcnt(0)
	ds_read2_b32 v[6:7], v104 offset0:33 offset1:41
	ds_read2_b32 v[8:9], v104 offset1:8
	ds_read2_b32 v[10:11], v104 offset0:66 offset1:74
	ds_read2_b32 v[12:13], v104 offset0:99 offset1:107
	ds_read2_b32 v[14:15], v104 offset0:132 offset1:140
	ds_read2_b32 v[16:17], v104 offset0:165 offset1:173
	ds_read2_b32 v[18:19], v104 offset0:198 offset1:206
	ds_read2_b32 v[20:21], v104 offset0:231 offset1:239
	s_mov_b32 s1, s7
	s_waitcnt lgkmcnt(6)
	v_cvt_pk_bf16_f32 v2, v8, v6
	v_or_b32_e32 v6, s2, v103
	v_lshl_add_u64 v[22:23], s[0:1], 1, v[76:77]
	v_lshlrev_b32_e32 v68, 11, v6
	s_waitcnt lgkmcnt(4)
	v_cvt_pk_bf16_f32 v3, v10, v12
	s_waitcnt lgkmcnt(2)
	v_cvt_pk_bf16_f32 v4, v14, v16
	s_waitcnt lgkmcnt(0)
	v_cvt_pk_bf16_f32 v5, v18, v20
	v_lshl_add_u64 v[24:25], v[22:23], 0, v[68:69]
	global_store_dwordx4 v[24:25], v[2:5], off
	v_or_b32_e32 v6, s2, v105
	v_lshlrev_b32_e32 v68, 11, v6
	v_cvt_pk_bf16_f32 v2, v9, v7
	v_cvt_pk_bf16_f32 v3, v11, v13
	v_cvt_pk_bf16_f32 v4, v15, v17
	v_cvt_pk_bf16_f32 v5, v19, v21
	ds_read2_b32 v[8:9], v104 offset0:49 offset1:57
	ds_read2_b32 v[10:11], v104 offset0:16 offset1:24
	ds_read2_b32 v[12:13], v104 offset0:82 offset1:90
	ds_read2_b32 v[14:15], v104 offset0:115 offset1:123
	ds_read2_b32 v[16:17], v104 offset0:148 offset1:156
	ds_read2_b32 v[18:19], v104 offset0:181 offset1:189
	ds_read2_b32 v[20:21], v104 offset0:214 offset1:222
	ds_read2_b32 v[24:25], v104 offset0:247 offset1:255
	v_lshl_add_u64 v[6:7], v[22:23], 0, v[68:69]
	global_store_dwordx4 v[6:7], v[2:5], off
	v_or_b32_e32 v6, s2, v106
	v_lshlrev_b32_e32 v68, 11, v6
	s_waitcnt lgkmcnt(6)
	v_cvt_pk_bf16_f32 v2, v10, v8
	s_waitcnt lgkmcnt(4)
	v_cvt_pk_bf16_f32 v3, v12, v14
	s_waitcnt lgkmcnt(2)
	v_cvt_pk_bf16_f32 v4, v16, v18
	s_waitcnt lgkmcnt(0)
	v_cvt_pk_bf16_f32 v5, v20, v24
	v_lshl_add_u64 v[6:7], v[22:23], 0, v[68:69]
	global_store_dwordx4 v[6:7], v[2:5], off
	v_or_b32_e32 v6, s2, v107
	v_lshlrev_b32_e32 v68, 11, v6
	v_cvt_pk_bf16_f32 v2, v11, v9
	v_cvt_pk_bf16_f32 v3, v13, v15
	v_cvt_pk_bf16_f32 v4, v17, v19
	v_cvt_pk_bf16_f32 v5, v21, v25
	v_lshl_add_u64 v[6:7], v[22:23], 0, v[68:69]
	global_store_dwordx4 v[6:7], v[2:5], off
	s_waitcnt lgkmcnt(0)
	s_mov_b64 s[0:1], 0
.LBB0_45:
	s_andn2_b64 vcc, exec, s[0:1]
	s_cbranch_vccnz .LBB0_47
	s_add_i32 s0, s26, 0xb580
	s_and_b32 s1, s0, 0xffff
	s_mul_i32 s1, s1, 0xe38f
	s_lshr_b32 s2, s1, 16
	s_lshr_b32 s1, s1, 22
	s_mulk_i32 s1, 0x48
	s_sub_i32 s0, s0, s1
	s_lshl_b32 s0, s0, 5
	s_and_b32 s0, s0, 0xffe0
	s_and_b32 s1, s2, 0xffc0
	v_or_b32_e32 v4, s1, v101
	s_lshl_b32 s6, s0, 2
	v_lshl_add_u64 v[2:3], v[78:79], 0, s[6:7]
	v_mul_u32_u24_e32 v68, 0x2400, v4
	v_lshl_add_u64 v[2:3], v[2:3], 0, v[68:69]
	v_add_co_u32_e32 v4, vcc, s81, v2
	s_mov_b32 s2, 0x9000
	s_nop 0
	v_addc_co_u32_e32 v5, vcc, 0, v3, vcc
	v_add_co_u32_e32 v6, vcc, s2, v2
	s_mov_b32 s2, 0xd000
	s_nop 0
	v_addc_co_u32_e32 v7, vcc, 0, v3, vcc
	v_add_co_u32_e32 v8, vcc, s2, v2
	s_mov_b32 s2, 0x1b000
	s_nop 0
	v_addc_co_u32_e32 v9, vcc, 0, v3, vcc
	v_add_co_u32_e32 v10, vcc, s83, v2
	s_lshl_b32 s6, s1, 1
	s_nop 0
	v_addc_co_u32_e32 v11, vcc, 0, v3, vcc
	v_add_co_u32_e32 v12, vcc, s84, v2
	s_nop 1
	v_addc_co_u32_e32 v13, vcc, 0, v3, vcc
	v_add_co_u32_e32 v14, vcc, s2, v2
	s_mov_b32 s2, 0x1f000
	s_nop 0
	v_addc_co_u32_e32 v15, vcc, 0, v3, vcc
	v_add_co_u32_e32 v16, vcc, s2, v2
	s_mov_b32 s2, 0x31000
	s_nop 0
	v_addc_co_u32_e32 v17, vcc, 0, v3, vcc
	global_load_dword v20, v[2:3], off
	global_load_dword v21, v[4:5], off offset:2048
	global_load_dword v22, v[6:7], off
	global_load_dword v23, v[8:9], off offset:2048
	global_load_dword v24, v[10:11], off
	global_load_dword v25, v[12:13], off offset:2048
	global_load_dword v26, v[14:15], off
	global_load_dword v27, v[16:17], off offset:2048
	v_add_co_u32_e32 v4, vcc, s86, v2
	s_nop 1
	v_addc_co_u32_e32 v5, vcc, 0, v3, vcc
	v_add_co_u32_e32 v6, vcc, s87, v2
	s_nop 1
	v_addc_co_u32_e32 v7, vcc, 0, v3, vcc
	v_add_co_u32_e32 v8, vcc, s88, v2
	s_nop 1
	v_addc_co_u32_e32 v9, vcc, 0, v3, vcc
	v_add_co_u32_e32 v10, vcc, s2, v2
	s_mov_b32 s2, 0x43000
	s_nop 0
	v_addc_co_u32_e32 v11, vcc, 0, v3, vcc
	v_add_co_u32_e32 v12, vcc, s89, v2
	s_nop 1
	v_addc_co_u32_e32 v13, vcc, 0, v3, vcc
	v_add_co_u32_e32 v14, vcc, s90, v2
	s_nop 1
	v_addc_co_u32_e32 v15, vcc, 0, v3, vcc
	v_add_co_u32_e32 v16, vcc, s91, v2
	s_nop 1
; #define LAS __attribute__((address_space(3)))
; #define GAS __attribute__((address_space(1)))
; DI unsigned pk2(float lo, float hi) { f32x2_t v = {lo, hi}; bf16x2_t b = __builtin_convertvector(v, bf16x2_t); return __builtin_bit_cast(unsigned, b); }
; DI void transpose_item(const GAS float* W, int K, int N, GAS bf16* WT, int vrow0, int scol0, int k0, LAS float* scr, int lane) {
;     ...
;     for (int i = 0; i < 32; ++i) wv[i] = __builtin_nontemporal_load(W + (size_t)(k0 + 2 * i + (lane >> 5)) * N + scol0 + (lane & 31));
; #pragma unroll
;     for (int i = 0; i < 32; ++i) scr[(2 * i + (lane >> 5)) * 33 + (lane & 31)] = wv[i];
;     asm volatile("s_waitcnt lgkmcnt(0)" ::: "memory");
;     const int c = lane & 7;
; #pragma unroll
;     for (int j = 0; j < 4; ++j) { const int n = (lane >> 3) + 8 * j; const LAS float* s = scr + (8 * c) * 33 + n;
;         u32x4 o; o.x = pk2(s[0 * 33], s[1 * 33]); o.y = pk2(s[2 * 33], s[3 * 33]); o.z = pk2(s[4 * 33], s[5 * 33]); o.w = pk2(s[6 * 33], s[7 * 33]);
;         *(GAS u32x4*)(WT + (size_t)(vrow0 + n) * K + k0 + 8 * c) = o; }
	v_addc_co_u32_e32 v17, vcc, 0, v3, vcc
	v_add_co_u32_e32 v18, vcc, s2, v2
	s_mov_b32 s2, 0x4c000
	s_nop 0
	v_addc_co_u32_e32 v19, vcc, 0, v3, vcc
	global_load_dword v28, v[4:5], off
	global_load_dword v29, v[6:7], off offset:2048
	global_load_dword v30, v[8:9], off
	global_load_dword v31, v[10:11], off offset:2048
	global_load_dword v32, v[12:13], off
	global_load_dword v33, v[14:15], off offset:2048
	global_load_dword v34, v[16:17], off
	global_load_dword v35, v[18:19], off offset:2048
	v_add_co_u32_e32 v4, vcc, s92, v2
	s_nop 1
	v_addc_co_u32_e32 v5, vcc, 0, v3, vcc
	v_add_co_u32_e32 v6, vcc, s2, v2
	s_mov_b32 s2, 0x55000
	s_nop 0
	v_addc_co_u32_e32 v7, vcc, 0, v3, vcc
	v_add_co_u32_e32 v8, vcc, s93, v2
	s_nop 1
	v_addc_co_u32_e32 v9, vcc, 0, v3, vcc
	v_add_co_u32_e32 v10, vcc, s2, v2
	s_mov_b32 s2, 0x5e000
	s_nop 0
	v_addc_co_u32_e32 v11, vcc, 0, v3, vcc
	v_add_co_u32_e32 v12, vcc, s94, v2
	s_nop 1
	v_addc_co_u32_e32 v13, vcc, 0, v3, vcc
	v_add_co_u32_e32 v14, vcc, s2, v2
	s_mov_b32 s2, 0x67000
	s_nop 0
	v_addc_co_u32_e32 v15, vcc, 0, v3, vcc
	v_add_co_u32_e32 v16, vcc, s95, v2
	s_nop 1
	v_addc_co_u32_e32 v17, vcc, 0, v3, vcc
	v_add_co_u32_e32 v18, vcc, s2, v2
	s_mov_b32 s2, 0x6c000
	s_nop 0
	v_addc_co_u32_e32 v19, vcc, 0, v3, vcc
	global_load_dword v36, v[4:5], off
	global_load_dword v37, v[6:7], off offset:2048
	global_load_dword v38, v[8:9], off
	global_load_dword v39, v[10:11], off offset:2048
	global_load_dword v40, v[12:13], off
	global_load_dword v41, v[14:15], off offset:2048
	global_load_dword v42, v[16:17], off
	s_nop 0
	global_load_dword v18, v[18:19], off offset:2048
	v_add_co_u32_e32 v4, vcc, s2, v2
	s_mov_b32 s2, 0x70000
	s_nop 0
	v_addc_co_u32_e32 v5, vcc, 0, v3, vcc
	v_add_co_u32_e32 v6, vcc, s2, v2
	s_mov_b32 s2, 0x75000
	s_nop 0
	v_addc_co_u32_e32 v7, vcc, 0, v3, vcc
	v_add_co_u32_e32 v8, vcc, s2, v2
	s_mov_b32 s2, 0x7e000
	s_nop 0
	v_addc_co_u32_e32 v9, vcc, 0, v3, vcc
	v_add_co_u32_e32 v10, vcc, s96, v2
	s_nop 1
	v_addc_co_u32_e32 v11, vcc, 0, v3, vcc
	v_add_co_u32_e32 v12, vcc, s2, v2
	s_mov_b32 s2, 0x82000
	s_nop 0
	v_addc_co_u32_e32 v13, vcc, 0, v3, vcc
	v_add_co_u32_e32 v14, vcc, s2, v2
	s_mov_b32 s2, 0x87000
	s_nop 0
	v_addc_co_u32_e32 v15, vcc, 0, v3, vcc
	v_add_co_u32_e32 v16, vcc, s2, v2
	s_mov_b32 s2, 0x8b000
	s_nop 0
	v_addc_co_u32_e32 v17, vcc, 0, v3, vcc
	v_add_co_u32_e32 v2, vcc, s2, v2
	s_nop 1
	v_addc_co_u32_e32 v3, vcc, 0, v3, vcc
	global_load_dword v4, v[4:5], off
	s_nop 0
	global_load_dword v5, v[6:7], off offset:2048
	s_nop 0
	global_load_dword v6, v[8:9], off
	global_load_dword v7, v[10:11], off offset:2048
	s_nop 0
	global_load_dword v8, v[12:13], off
	global_load_dword v9, v[14:15], off offset:2048
	global_load_dword v10, v[16:17], off
	s_nop 0
	global_load_dword v2, v[2:3], off offset:2048
	v_add_u32_e32 v3, 0x400, v102
	s_waitcnt vmcnt(30)
	ds_write2_b32 v102, v20, v21 offset1:66
	s_waitcnt vmcnt(28)
	ds_write2_b32 v102, v22, v23 offset0:132 offset1:198
	s_waitcnt vmcnt(26)
	ds_write2_b32 v3, v24, v25 offset0:8 offset1:74
	s_waitcnt vmcnt(24)
	ds_write2_b32 v3, v26, v27 offset0:140 offset1:206
	v_add_u32_e32 v3, 0x800, v102
	s_waitcnt vmcnt(22)
	ds_write2_b32 v3, v28, v29 offset0:16 offset1:82
	s_waitcnt vmcnt(20)
	ds_write2_b32 v3, v30, v31 offset0:148 offset1:214
	v_add_u32_e32 v3, 0xc00, v102
	s_waitcnt vmcnt(18)
	ds_write2_b32 v3, v32, v33 offset0:24 offset1:90
	s_waitcnt vmcnt(16)
	ds_write2_b32 v3, v34, v35 offset0:156 offset1:222
	v_add_u32_e32 v3, 0x1000, v102
	s_waitcnt vmcnt(14)
	ds_write2_b32 v3, v36, v37 offset0:32 offset1:98
	s_waitcnt vmcnt(12)
	ds_write2_b32 v3, v38, v39 offset0:164 offset1:230
	v_add_u32_e32 v3, 0x1400, v102
	s_waitcnt vmcnt(10)
	ds_write2_b32 v3, v40, v41 offset0:40 offset1:106
	s_waitcnt vmcnt(8)
	ds_write2_b32 v3, v42, v18 offset0:172 offset1:238
	v_add_u32_e32 v3, 0x1800, v102
	s_waitcnt vmcnt(6)
	ds_write2_b32 v3, v4, v5 offset0:48 offset1:114
	s_waitcnt vmcnt(4)
	ds_write2_b32 v3, v6, v7 offset0:180 offset1:246
	v_add_u32_e32 v3, 0x1c00, v102
	s_waitcnt vmcnt(2)
	ds_write2_b32 v3, v8, v9 offset0:56 offset1:122
	s_waitcnt vmcnt(0)
	ds_write2_b32 v3, v10, v2 offset0:188 offset1:254
	s_waitcnt lgkmcnt(0)
	ds_read2_b32 v[6:7], v104 offset0:33 offset1:41
	ds_read2_b32 v[8:9], v104 offset1:8
	ds_read2_b32 v[10:11], v104 offset0:66 offset1:74
	ds_read2_b32 v[12:13], v104 offset0:99 offset1:107
	ds_read2_b32 v[14:15], v104 offset0:132 offset1:140
	ds_read2_b32 v[16:17], v104 offset0:165 offset1:173
	ds_read2_b32 v[18:19], v104 offset0:198 offset1:206
	ds_read2_b32 v[20:21], v104 offset0:231 offset1:239
	s_waitcnt lgkmcnt(6)
	v_cvt_pk_bf16_f32 v2, v8, v6
	v_or_b32_e32 v6, s0, v103
	v_lshl_add_u64 v[22:23], v[80:81], 0, s[6:7]
	v_lshlrev_b32_e32 v68, 11, v6
	s_waitcnt lgkmcnt(4)
	v_cvt_pk_bf16_f32 v3, v10, v12
	s_waitcnt lgkmcnt(2)
	v_cvt_pk_bf16_f32 v4, v14, v16
	s_waitcnt lgkmcnt(0)
	v_cvt_pk_bf16_f32 v5, v18, v20
	v_lshl_add_u64 v[24:25], v[22:23], 0, v[68:69]
	global_store_dwordx4 v[24:25], v[2:5], off
	v_or_b32_e32 v6, s0, v105
	v_lshlrev_b32_e32 v68, 11, v6
	v_cvt_pk_bf16_f32 v2, v9, v7
	v_cvt_pk_bf16_f32 v3, v11, v13
	v_cvt_pk_bf16_f32 v4, v15, v17
	v_cvt_pk_bf16_f32 v5, v19, v21
	ds_read2_b32 v[8:9], v104 offset0:49 offset1:57
	ds_read2_b32 v[10:11], v104 offset0:16 offset1:24
	ds_read2_b32 v[12:13], v104 offset0:82 offset1:90
	ds_read2_b32 v[14:15], v104 offset0:115 offset1:123
	ds_read2_b32 v[16:17], v104 offset0:148 offset1:156
	ds_read2_b32 v[18:19], v104 offset0:181 offset1:189
	ds_read2_b32 v[20:21], v104 offset0:214 offset1:222
	ds_read2_b32 v[24:25], v104 offset0:247 offset1:255
	v_lshl_add_u64 v[6:7], v[22:23], 0, v[68:69]
	global_store_dwordx4 v[6:7], v[2:5], off
	v_or_b32_e32 v6, s0, v106
	v_lshlrev_b32_e32 v68, 11, v6
	s_waitcnt lgkmcnt(6)
	v_cvt_pk_bf16_f32 v2, v10, v8
	s_waitcnt lgkmcnt(4)
	v_cvt_pk_bf16_f32 v3, v12, v14
	s_waitcnt lgkmcnt(2)
	v_cvt_pk_bf16_f32 v4, v16, v18
	s_waitcnt lgkmcnt(0)
	v_cvt_pk_bf16_f32 v5, v20, v24
	v_lshl_add_u64 v[6:7], v[22:23], 0, v[68:69]
	global_store_dwordx4 v[6:7], v[2:5], off
	v_or_b32_e32 v6, s0, v107
	v_lshlrev_b32_e32 v68, 11, v6
	v_cvt_pk_bf16_f32 v2, v11, v9
	v_cvt_pk_bf16_f32 v3, v13, v15
	v_cvt_pk_bf16_f32 v4, v17, v19
	v_cvt_pk_bf16_f32 v5, v21, v25
	v_lshl_add_u64 v[6:7], v[22:23], 0, v[68:69]
	global_store_dwordx4 v[6:7], v[2:5], off
	s_waitcnt lgkmcnt(0)

; DI void transpose_item(const GAS float* W, int K, int N, GAS bf16* WT, int vrow0, int scol0, int k0, LAS float* scr, int lane) {
;     ...
;     for (int i = 0; i < 32; ++i) wv[i] = __builtin_nontemporal_load(W + (size_t)(k0 + 2 * i + (lane >> 5)) * N + scol0 + (lane & 31));
; DI void phase_prep(const Ctx& C) {
;     ...
;             if (it < T_EVO) { const int kb = it / 32, nb = it % 32; transpose_item(INP(I_EVWOUT), 1024, 1024, WSP(bf16, WS_WEVOUT), 32 * nb, 32 * nb, 64 * kb, scr, lane); continue; }
.LBB0_48:
	s_andn2_b64 vcc, exec, s[0:1]
	s_cbranch_vccnz .LBB0_50
	s_lshl_b32 s0, s26, 5
	s_and_b32 s2, s0, 0x3e0
	s_lshl_b32 s0, s26, 1
	s_and_b32 s0, s0, 0xffc0
	s_add_i32 s0, s0, 0xffff6f00
	v_or_b32_e32 v68, s0, v101
	s_lshl_b32 s6, s2, 2
	v_or_b32_e32 v6, 2, v68
	v_mov_b32_e32 v7, v69
	v_or_b32_e32 v8, 4, v68
	v_mov_b32_e32 v9, v69
	v_or_b32_e32 v10, 6, v68
	v_mov_b32_e32 v11, v69
	v_or_b32_e32 v12, 8, v68
	v_mov_b32_e32 v13, v69
	v_or_b32_e32 v14, 10, v68
	v_mov_b32_e32 v15, v69
	v_or_b32_e32 v16, 12, v68
	v_mov_b32_e32 v17, v69
	v_lshl_add_u64 v[2:3], v[82:83], 0, s[6:7]
	v_lshlrev_b64 v[4:5], 12, v[68:69]
	v_lshlrev_b64 v[6:7], 12, v[6:7]
	v_lshlrev_b64 v[8:9], 12, v[8:9]
	v_lshlrev_b64 v[10:11], 12, v[10:11]
	v_lshlrev_b64 v[12:13], 12, v[12:13]
	v_lshlrev_b64 v[14:15], 12, v[14:15]
	v_lshlrev_b64 v[16:17], 12, v[16:17]
	v_or_b32_e32 v18, 14, v68
	v_mov_b32_e32 v19, v69
	v_lshl_add_u64 v[4:5], v[2:3], 0, v[4:5]
	v_lshl_add_u64 v[6:7], v[2:3], 0, v[6:7]
	v_lshl_add_u64 v[8:9], v[2:3], 0, v[8:9]
	v_lshl_add_u64 v[10:11], v[2:3], 0, v[10:11]
	v_lshl_add_u64 v[12:13], v[2:3], 0, v[12:13]
	v_lshl_add_u64 v[14:15], v[2:3], 0, v[14:15]
	v_lshl_add_u64 v[16:17], v[2:3], 0, v[16:17]
	v_lshlrev_b64 v[18:19], 12, v[18:19]
	v_lshl_add_u64 v[18:19], v[2:3], 0, v[18:19]
	global_load_dword v20, v[4:5], off
	global_load_dword v21, v[6:7], off
	global_load_dword v22, v[8:9], off
	global_load_dword v23, v[10:11], off
	global_load_dword v24, v[12:13], off
	global_load_dword v25, v[14:15], off
	global_load_dword v26, v[16:17], off
	global_load_dword v27, v[18:19], off
	v_or_b32_e32 v4, 16, v68
	v_mov_b32_e32 v5, v69
	v_or_b32_e32 v6, 18, v68
	v_mov_b32_e32 v7, v69
	v_or_b32_e32 v8, 20, v68
	v_mov_b32_e32 v9, v69
	v_or_b32_e32 v10, 22, v68
	v_mov_b32_e32 v11, v69
	v_or_b32_e32 v12, 24, v68
	v_mov_b32_e32 v13, v69
	v_or_b32_e32 v14, 26, v68
	v_mov_b32_e32 v15, v69
	v_or_b32_e32 v16, 28, v68
	v_mov_b32_e32 v17, v69
	v_lshlrev_b64 v[4:5], 12, v[4:5]
	v_lshlrev_b64 v[6:7], 12, v[6:7]
	v_lshlrev_b64 v[8:9], 12, v[8:9]
	v_lshlrev_b64 v[10:11], 12, v[10:11]
	v_lshlrev_b64 v[12:13], 12, v[12:13]
	v_lshlrev_b64 v[14:15], 12, v[14:15]
	v_lshlrev_b64 v[16:17], 12, v[16:17]
	v_or_b32_e32 v18, 30, v68
	v_mov_b32_e32 v19, v69
	v_lshl_add_u64 v[4:5], v[2:3], 0, v[4:5]
	v_lshl_add_u64 v[6:7], v[2:3], 0, v[6:7]
	v_lshl_add_u64 v[8:9], v[2:3], 0, v[8:9]
	v_lshl_add_u64 v[10:11], v[2:3], 0, v[10:11]
	v_lshl_add_u64 v[12:13], v[2:3], 0, v[12:13]
	v_lshl_add_u64 v[14:15], v[2:3], 0, v[14:15]
	v_lshl_add_u64 v[16:17], v[2:3], 0, v[16:17]
	v_lshlrev_b64 v[18:19], 12, v[18:19]
	v_lshl_add_u64 v[18:19], v[2:3], 0, v[18:19]
	global_load_dword v28, v[4:5], off
	global_load_dword v29, v[6:7], off
	global_load_dword v30, v[8:9], off
	global_load_dword v31, v[10:11], off
	global_load_dword v32, v[12:13], off
	global_load_dword v33, v[14:15], off
	global_load_dword v34, v[16:17], off
	global_load_dword v35, v[18:19], off
	v_or_b32_e32 v4, 32, v68
	v_mov_b32_e32 v5, v69
	v_or_b32_e32 v6, 34, v68
	v_mov_b32_e32 v7, v69
	v_or_b32_e32 v8, 36, v68
	v_mov_b32_e32 v9, v69
	v_or_b32_e32 v10, 38, v68
	v_mov_b32_e32 v11, v69
	v_or_b32_e32 v12, 40, v68
	v_mov_b32_e32 v13, v69
	v_or_b32_e32 v14, 42, v68
	v_mov_b32_e32 v15, v69
	v_or_b32_e32 v16, 44, v68
	v_mov_b32_e32 v17, v69
	v_lshlrev_b64 v[4:5], 12, v[4:5]
	v_lshlrev_b64 v[6:7], 12, v[6:7]
	v_lshlrev_b64 v[8:9], 12, v[8:9]
	v_lshlrev_b64 v[10:11], 12, v[10:11]
	v_lshlrev_b64 v[12:13], 12, v[12:13]
	v_lshlrev_b64 v[14:15], 12, v[14:15]
	v_lshlrev_b64 v[16:17], 12, v[16:17]
	v_or_b32_e32 v18, 46, v68
	v_mov_b32_e32 v19, v69
	v_lshl_add_u64 v[4:5], v[2:3], 0, v[4:5]
	v_lshl_add_u64 v[6:7], v[2:3], 0, v[6:7]
	v_lshl_add_u64 v[8:9], v[2:3], 0, v[8:9]
	v_lshl_add_u64 v[10:11], v[2:3], 0, v[10:11]
	v_lshl_add_u64 v[12:13], v[2:3], 0, v[12:13]
	v_lshl_add_u64 v[14:15], v[2:3], 0, v[14:15]
	v_lshl_add_u64 v[16:17], v[2:3], 0, v[16:17]
	v_lshlrev_b64 v[18:19], 12, v[18:19]
	v_lshl_add_u64 v[18:19], v[2:3], 0, v[18:19]
	global_load_dword v36, v[4:5], off
	global_load_dword v37, v[6:7], off
	global_load_dword v38, v[8:9], off
	global_load_dword v39, v[10:11], off
	global_load_dword v40, v[12:13], off
	global_load_dword v41, v[14:15], off
	global_load_dword v42, v[16:17], off
	global_load_dword v43, v[18:19], off
	v_or_b32_e32 v4, 48, v68
	v_mov_b32_e32 v5, v69
	v_or_b32_e32 v6, 50, v68
	v_mov_b32_e32 v7, v69
	v_or_b32_e32 v8, 52, v68
	v_mov_b32_e32 v9, v69
	v_or_b32_e32 v10, 54, v68
	v_mov_b32_e32 v11, v69
	v_or_b32_e32 v12, 56, v68
	v_mov_b32_e32 v13, v69
	v_or_b32_e32 v14, 58, v68
	v_mov_b32_e32 v15, v69
	v_or_b32_e32 v16, 60, v68
	v_mov_b32_e32 v17, v69
	v_or_b32_e32 v68, 62, v68
	v_lshlrev_b64 v[4:5], 12, v[4:5]
	v_lshlrev_b64 v[6:7], 12, v[6:7]
	v_lshlrev_b64 v[8:9], 12, v[8:9]
	v_lshlrev_b64 v[10:11], 12, v[10:11]
	v_lshlrev_b64 v[12:13], 12, v[12:13]
	v_lshlrev_b64 v[14:15], 12, v[14:15]
	v_lshlrev_b64 v[16:17], 12, v[16:17]
	v_lshlrev_b64 v[18:19], 12, v[68:69]
	v_lshl_add_u64 v[4:5], v[2:3], 0, v[4:5]
	v_lshl_add_u64 v[6:7], v[2:3], 0, v[6:7]
	v_lshl_add_u64 v[8:9], v[2:3], 0, v[8:9]
	v_lshl_add_u64 v[10:11], v[2:3], 0, v[10:11]
	v_lshl_add_u64 v[12:13], v[2:3], 0, v[12:13]
	v_lshl_add_u64 v[14:15], v[2:3], 0, v[14:15]
	v_lshl_add_u64 v[16:17], v[2:3], 0, v[16:17]
	v_lshl_add_u64 v[2:3], v[2:3], 0, v[18:19]
	global_load_dword v4, v[4:5], off
	s_nop 0
	global_load_dword v5, v[6:7], off
	s_nop 0
	global_load_dword v6, v[8:9], off
	global_load_dword v7, v[10:11], off
	s_nop 0
	global_load_dword v8, v[12:13], off
	global_load_dword v9, v[14:15], off
	global_load_dword v10, v[16:17], off
	s_nop 0
	global_load_dword v2, v[2:3], off
	v_add_u32_e32 v3, 0x400, v102
	s_waitcnt vmcnt(30)
; #define LAS __attribute__((address_space(3)))
; #define GAS __attribute__((address_space(1)))
; DI unsigned pk2(float lo, float hi) { f32x2_t v = {lo, hi}; bf16x2_t b = __builtin_convertvector(v, bf16x2_t); return __builtin_bit_cast(unsigned, b); }
; DI void transpose_item(const GAS float* W, int K, int N, GAS bf16* WT, int vrow0, int scol0, int k0, LAS float* scr, int lane) {
;     ...
; #pragma unroll
;     for (int i = 0; i < 32; ++i) scr[(2 * i + (lane >> 5)) * 33 + (lane & 31)] = wv[i];
;     asm volatile("s_waitcnt lgkmcnt(0)" ::: "memory");
;     const int c = lane & 7;
; #pragma unroll
;     for (int j = 0; j < 4; ++j) { const int n = (lane >> 3) + 8 * j; const LAS float* s = scr + (8 * c) * 33 + n;
;         u32x4 o; o.x = pk2(s[0 * 33], s[1 * 33]); o.y = pk2(s[2 * 33], s[3 * 33]); o.z = pk2(s[4 * 33], s[5 * 33]); o.w = pk2(s[6 * 33], s[7 * 33]);
;         *(GAS u32x4*)(WT + (size_t)(vrow0 + n) * K + k0 + 8 * c) = o; }
	ds_write2_b32 v102, v20, v21 offset1:66
	s_waitcnt vmcnt(28)
	ds_write2_b32 v102, v22, v23 offset0:132 offset1:198
	s_waitcnt vmcnt(26)
	ds_write2_b32 v3, v24, v25 offset0:8 offset1:74
	s_waitcnt vmcnt(24)
	ds_write2_b32 v3, v26, v27 offset0:140 offset1:206
	v_add_u32_e32 v3, 0x800, v102
	s_waitcnt vmcnt(22)
	ds_write2_b32 v3, v28, v29 offset0:16 offset1:82
	s_waitcnt vmcnt(20)
	ds_write2_b32 v3, v30, v31 offset0:148 offset1:214
	v_add_u32_e32 v3, 0xc00, v102
	s_waitcnt vmcnt(18)
	ds_write2_b32 v3, v32, v33 offset0:24 offset1:90
	s_waitcnt vmcnt(16)
	ds_write2_b32 v3, v34, v35 offset0:156 offset1:222
	v_add_u32_e32 v3, 0x1000, v102
	s_waitcnt vmcnt(14)
	ds_write2_b32 v3, v36, v37 offset0:32 offset1:98
	s_waitcnt vmcnt(12)
	ds_write2_b32 v3, v38, v39 offset0:164 offset1:230
	v_add_u32_e32 v3, 0x1400, v102
	s_waitcnt vmcnt(10)
	ds_write2_b32 v3, v40, v41 offset0:40 offset1:106
	s_waitcnt vmcnt(8)
	ds_write2_b32 v3, v42, v43 offset0:172 offset1:238
	v_add_u32_e32 v3, 0x1800, v102
	s_waitcnt vmcnt(6)
	ds_write2_b32 v3, v4, v5 offset0:48 offset1:114
	s_waitcnt vmcnt(4)
	ds_write2_b32 v3, v6, v7 offset0:180 offset1:246
	v_add_u32_e32 v3, 0x1c00, v102
	s_waitcnt vmcnt(2)
	ds_write2_b32 v3, v8, v9 offset0:56 offset1:122
	s_waitcnt vmcnt(0)
	ds_write2_b32 v3, v10, v2 offset0:188 offset1:254
	s_waitcnt lgkmcnt(0)
	ds_read2_b32 v[6:7], v104 offset0:33 offset1:41
	ds_read2_b32 v[8:9], v104 offset1:8
	ds_read2_b32 v[10:11], v104 offset0:66 offset1:74
	ds_read2_b32 v[12:13], v104 offset0:99 offset1:107
	ds_read2_b32 v[14:15], v104 offset0:132 offset1:140
	ds_read2_b32 v[16:17], v104 offset0:165 offset1:173
	ds_read2_b32 v[18:19], v104 offset0:198 offset1:206
	ds_read2_b32 v[20:21], v104 offset0:231 offset1:239
	s_mov_b32 s1, s7
	s_waitcnt lgkmcnt(6)
	v_cvt_pk_bf16_f32 v2, v8, v6
	v_or_b32_e32 v6, s2, v103
	v_lshl_add_u64 v[22:23], s[0:1], 1, v[84:85]
	v_lshlrev_b32_e32 v68, 11, v6
	s_waitcnt lgkmcnt(4)
	v_cvt_pk_bf16_f32 v3, v10, v12
	s_waitcnt lgkmcnt(2)
	v_cvt_pk_bf16_f32 v4, v14, v16
	s_waitcnt lgkmcnt(0)
	v_cvt_pk_bf16_f32 v5, v18, v20
	v_lshl_add_u64 v[24:25], v[22:23], 0, v[68:69]
	global_store_dwordx4 v[24:25], v[2:5], off
	v_or_b32_e32 v6, s2, v105
	v_lshlrev_b32_e32 v68, 11, v6
	v_cvt_pk_bf16_f32 v2, v9, v7
	v_cvt_pk_bf16_f32 v3, v11, v13
	v_cvt_pk_bf16_f32 v4, v15, v17
	v_cvt_pk_bf16_f32 v5, v19, v21
	ds_read2_b32 v[8:9], v104 offset0:49 offset1:57
	ds_read2_b32 v[10:11], v104 offset0:16 offset1:24
	ds_read2_b32 v[12:13], v104 offset0:82 offset1:90
	ds_read2_b32 v[14:15], v104 offset0:115 offset1:123
	ds_read2_b32 v[16:17], v104 offset0:148 offset1:156
	ds_read2_b32 v[18:19], v104 offset0:181 offset1:189
	ds_read2_b32 v[20:21], v104 offset0:214 offset1:222
	ds_read2_b32 v[24:25], v104 offset0:247 offset1:255
	v_lshl_add_u64 v[6:7], v[22:23], 0, v[68:69]
	global_store_dwordx4 v[6:7], v[2:5], off
	v_or_b32_e32 v6, s2, v106
	v_lshlrev_b32_e32 v68, 11, v6
	s_waitcnt lgkmcnt(6)
	v_cvt_pk_bf16_f32 v2, v10, v8
	s_waitcnt lgkmcnt(4)
	v_cvt_pk_bf16_f32 v3, v12, v14
	s_waitcnt lgkmcnt(2)
	v_cvt_pk_bf16_f32 v4, v16, v18
	s_waitcnt lgkmcnt(0)
	v_cvt_pk_bf16_f32 v5, v20, v24
	v_lshl_add_u64 v[6:7], v[22:23], 0, v[68:69]
	global_store_dwordx4 v[6:7], v[2:5], off
	v_or_b32_e32 v6, s2, v107
	v_lshlrev_b32_e32 v68, 11, v6
	v_cvt_pk_bf16_f32 v2, v11, v9
	v_cvt_pk_bf16_f32 v3, v13, v15
	v_cvt_pk_bf16_f32 v4, v17, v19
	v_cvt_pk_bf16_f32 v5, v21, v25
	v_lshl_add_u64 v[6:7], v[22:23], 0, v[68:69]
	global_store_dwordx4 v[6:7], v[2:5], off
	s_waitcnt lgkmcnt(0)

; DI int glu_map128(int v, int half_off) { return ((v & 255) >= 128 ? half_off : 0) + 128 * (v >> 8) + (v & 127); }
; DI void transpose_item(const GAS float* W, int K, int N, GAS bf16* WT, int vrow0, int scol0, int k0, LAS float* scr, int lane) {
;     ...
;     for (int i = 0; i < 32; ++i) wv[i] = __builtin_nontemporal_load(W + (size_t)(k0 + 2 * i + (lane >> 5)) * N + scol0 + (lane & 31));
; DI void phase_prep(const Ctx& C) {
;     ...
;             if (it < T_EVG) { const int kb = it / 32, nb = it % 32;
;                 transpose_item(INP(I_EVWIN), 1024, 1536, WSP(bf16, WS_WEVIN), 1024 + 32 * nb, 512 + glu_map128(32 * nb, 512), 64 * kb, scr, lane); continue; }
.LBB0_51:
	s_andn2_b64 vcc, exec, s[0:1]
	s_cbranch_vccnz .LBB0_53
	s_lshl_b32 s1, s26, 5
	s_lshl_b32 s2, s26, 4
	s_lshl_b32 s0, s26, 7
	s_and_b32 s2, s2, 0x180
	s_and_b32 s3, s1, 0x60
	s_and_b32 s0, s0, 0x200
	s_or_b32 s2, s2, s3
	s_or_b32 s2, s2, s0
	s_lshl_b32 s0, s26, 1
	s_and_b32 s0, s0, 0xffc0
	s_add_i32 s0, s0, 0xffff7300
	v_or_b32_e32 v4, s0, v101
	s_lshl_b32 s6, s2, 2
	v_lshl_add_u64 v[2:3], v[88:89], 0, s[6:7]
	v_mul_i32_i24_e32 v68, 0x1800, v4
	v_lshl_add_u64 v[2:3], v[2:3], 0, v[68:69]
	s_movk_i32 s2, 0x3000
	v_add_co_u32_e32 v4, vcc, s2, v2
	s_mov_b32 s2, 0x9000
	s_nop 0
	v_addc_co_u32_e32 v5, vcc, 0, v3, vcc
	v_add_co_u32_e32 v6, vcc, s97, v2
	s_and_b32 s1, s1, 0x3e0
	s_nop 0
	v_addc_co_u32_e32 v7, vcc, 0, v3, vcc
	v_add_co_u32_e32 v8, vcc, s2, v2
	s_mov_b32 s2, 0xf000
	s_nop 0
	v_addc_co_u32_e32 v9, vcc, 0, v3, vcc
	v_add_co_u32_e32 v10, vcc, s65, v2
	s_nop 1
	v_addc_co_u32_e32 v11, vcc, 0, v3, vcc
	v_add_co_u32_e32 v12, vcc, s2, v2
	s_mov_b32 s2, 0x15000
	s_nop 0
	v_addc_co_u32_e32 v13, vcc, 0, v3, vcc
	v_add_co_u32_e32 v14, vcc, s83, v2
	s_nop 1
	v_addc_co_u32_e32 v15, vcc, 0, v3, vcc
	v_add_co_u32_e32 v16, vcc, s2, v2
	s_mov_b32 s2, 0x1b000
	s_nop 0
	v_addc_co_u32_e32 v17, vcc, 0, v3, vcc
	global_load_dword v20, v[2:3], off offset:2048
	global_load_dword v21, v[4:5], off offset:2048
	global_load_dword v22, v[6:7], off offset:2048
	global_load_dword v23, v[8:9], off offset:2048
	global_load_dword v24, v[10:11], off offset:2048
	global_load_dword v25, v[12:13], off offset:2048
	global_load_dword v26, v[14:15], off offset:2048
	global_load_dword v27, v[16:17], off offset:2048
	v_add_co_u32_e32 v4, vcc, s66, v2
	s_nop 1
	v_addc_co_u32_e32 v5, vcc, 0, v3, vcc
	v_add_co_u32_e32 v6, vcc, s2, v2
	s_mov_b32 s2, 0x27000
	s_nop 0
	v_addc_co_u32_e32 v7, vcc, 0, v3, vcc
	v_add_co_u32_e32 v8, vcc, s67, v2
	s_nop 1
	v_addc_co_u32_e32 v9, vcc, 0, v3, vcc
	v_add_co_u32_e32 v10, vcc, s74, v2
	s_nop 1
	v_addc_co_u32_e32 v11, vcc, 0, v3, vcc
	v_add_co_u32_e32 v12, vcc, s86, v2
	s_nop 1
	v_addc_co_u32_e32 v13, vcc, 0, v3, vcc
	v_add_co_u32_e32 v14, vcc, s2, v2
	s_mov_b32 s2, 0x33000
	s_nop 0
	v_addc_co_u32_e32 v15, vcc, 0, v3, vcc
	v_add_co_u32_e32 v16, vcc, s75, v2
	s_nop 1
	v_addc_co_u32_e32 v17, vcc, 0, v3, vcc
	v_add_co_u32_e32 v18, vcc, s88, v2
	s_nop 1
	v_addc_co_u32_e32 v19, vcc, 0, v3, vcc
	global_load_dword v28, v[4:5], off offset:2048
	global_load_dword v29, v[6:7], off offset:2048
	global_load_dword v30, v[8:9], off offset:2048
	global_load_dword v31, v[10:11], off offset:2048
	global_load_dword v32, v[12:13], off offset:2048
	global_load_dword v33, v[14:15], off offset:2048
	global_load_dword v34, v[16:17], off offset:2048
	global_load_dword v35, v[18:19], off offset:2048
	v_add_co_u32_e32 v4, vcc, s76, v2
	s_nop 1
	v_addc_co_u32_e32 v5, vcc, 0, v3, vcc
	v_add_co_u32_e32 v6, vcc, s2, v2
	s_mov_b32 s2, 0x39000
	s_nop 0
	v_addc_co_u32_e32 v7, vcc, 0, v3, vcc
	v_add_co_u32_e32 v8, vcc, s89, v2
	s_nop 1
	v_addc_co_u32_e32 v9, vcc, 0, v3, vcc
	v_add_co_u32_e32 v10, vcc, s2, v2
	s_mov_b32 s2, 0x45000
	s_nop 0
	v_addc_co_u32_e32 v11, vcc, 0, v3, vcc
	v_add_co_u32_e32 v12, vcc, s77, v2
	s_nop 1
	v_addc_co_u32_e32 v13, vcc, 0, v3, vcc
	v_add_co_u32_e32 v14, vcc, s91, v2
	s_nop 1
	v_addc_co_u32_e32 v15, vcc, 0, v3, vcc
	v_add_co_u32_e32 v16, vcc, s78, v2
	s_nop 1
	v_addc_co_u32_e32 v17, vcc, 0, v3, vcc
	v_add_co_u32_e32 v18, vcc, s2, v2
	s_mov_b32 s2, 0x4b000
	s_nop 0
	v_addc_co_u32_e32 v19, vcc, 0, v3, vcc
	global_load_dword v36, v[4:5], off offset:2048
	global_load_dword v37, v[6:7], off offset:2048
	global_load_dword v38, v[8:9], off offset:2048
	global_load_dword v39, v[10:11], off offset:2048
	global_load_dword v40, v[12:13], off offset:2048
	global_load_dword v41, v[14:15], off offset:2048
	global_load_dword v42, v[16:17], off offset:2048
	s_nop 0
	global_load_dword v18, v[18:19], off offset:2048
	v_add_co_u32_e32 v4, vcc, s92, v2
	s_nop 1
	v_addc_co_u32_e32 v5, vcc, 0, v3, vcc
	v_add_co_u32_e32 v6, vcc, s2, v2
	s_mov_b32 s2, 0x4e000
	s_nop 0
	v_addc_co_u32_e32 v7, vcc, 0, v3, vcc
	v_add_co_u32_e32 v8, vcc, s2, v2
	s_mov_b32 s2, 0x54000
	s_nop 0
	v_addc_co_u32_e32 v9, vcc, 0, v3, vcc
	v_add_co_u32_e32 v10, vcc, s93, v2
	s_nop 1
	v_addc_co_u32_e32 v11, vcc, 0, v3, vcc
	v_add_co_u32_e32 v12, vcc, s2, v2
	s_mov_b32 s2, 0x57000
	s_nop 0
	v_addc_co_u32_e32 v13, vcc, 0, v3, vcc
	v_add_co_u32_e32 v14, vcc, s2, v2
	s_mov_b32 s2, 0x5d000
	s_nop 0
	v_addc_co_u32_e32 v15, vcc, 0, v3, vcc
	v_add_co_u32_e32 v16, vcc, s94, v2
	s_nop 1
	v_addc_co_u32_e32 v17, vcc, 0, v3, vcc
	v_add_co_u32_e32 v2, vcc, s2, v2
	s_or_b32 s2, s1, 0x400
	s_nop 0
	v_addc_co_u32_e32 v3, vcc, 0, v3, vcc
	global_load_dword v4, v[4:5], off offset:2048
	s_nop 0
	global_load_dword v5, v[6:7], off offset:2048
	s_nop 0
	global_load_dword v6, v[8:9], off offset:2048
	global_load_dword v7, v[10:11], off offset:2048
	s_nop 0
	global_load_dword v8, v[12:13], off offset:2048
	global_load_dword v9, v[14:15], off offset:2048
	global_load_dword v10, v[16:17], off offset:2048
	s_nop 0
	global_load_dword v2, v[2:3], off offset:2048
	v_add_u32_e32 v3, 0x400, v102
	s_waitcnt vmcnt(30)
; #define LAS __attribute__((address_space(3)))
; #define GAS __attribute__((address_space(1)))
; DI unsigned pk2(float lo, float hi) { f32x2_t v = {lo, hi}; bf16x2_t b = __builtin_convertvector(v, bf16x2_t); return __builtin_bit_cast(unsigned, b); }
; DI void transpose_item(const GAS float* W, int K, int N, GAS bf16* WT, int vrow0, int scol0, int k0, LAS float* scr, int lane) {
;     ...
; #pragma unroll
;     for (int i = 0; i < 32; ++i) scr[(2 * i + (lane >> 5)) * 33 + (lane & 31)] = wv[i];
;     asm volatile("s_waitcnt lgkmcnt(0)" ::: "memory");
;     const int c = lane & 7;
; #pragma unroll
;     for (int j = 0; j < 4; ++j) { const int n = (lane >> 3) + 8 * j; const LAS float* s = scr + (8 * c) * 33 + n;
;         u32x4 o; o.x = pk2(s[0 * 33], s[1 * 33]); o.y = pk2(s[2 * 33], s[3 * 33]); o.z = pk2(s[4 * 33], s[5 * 33]); o.w = pk2(s[6 * 33], s[7 * 33]);
;         *(GAS u32x4*)(WT + (size_t)(vrow0 + n) * K + k0 + 8 * c) = o; }
	ds_write2_b32 v102, v20, v21 offset1:66
	s_waitcnt vmcnt(28)
	ds_write2_b32 v102, v22, v23 offset0:132 offset1:198
	s_waitcnt vmcnt(26)
	ds_write2_b32 v3, v24, v25 offset0:8 offset1:74
	s_waitcnt vmcnt(24)
	ds_write2_b32 v3, v26, v27 offset0:140 offset1:206
	v_add_u32_e32 v3, 0x800, v102
	s_waitcnt vmcnt(22)
	ds_write2_b32 v3, v28, v29 offset0:16 offset1:82
	s_waitcnt vmcnt(20)
	ds_write2_b32 v3, v30, v31 offset0:148 offset1:214
	v_add_u32_e32 v3, 0xc00, v102
	s_waitcnt vmcnt(18)
	ds_write2_b32 v3, v32, v33 offset0:24 offset1:90
	s_waitcnt vmcnt(16)
	ds_write2_b32 v3, v34, v35 offset0:156 offset1:222
	v_add_u32_e32 v3, 0x1000, v102
	s_waitcnt vmcnt(14)
	ds_write2_b32 v3, v36, v37 offset0:32 offset1:98
	s_waitcnt vmcnt(12)
	ds_write2_b32 v3, v38, v39 offset0:164 offset1:230
	v_add_u32_e32 v3, 0x1400, v102
	s_waitcnt vmcnt(10)
	ds_write2_b32 v3, v40, v41 offset0:40 offset1:106
	s_waitcnt vmcnt(8)
	ds_write2_b32 v3, v42, v18 offset0:172 offset1:238
	v_add_u32_e32 v3, 0x1800, v102
	s_waitcnt vmcnt(6)
	ds_write2_b32 v3, v4, v5 offset0:48 offset1:114
	s_waitcnt vmcnt(4)
	ds_write2_b32 v3, v6, v7 offset0:180 offset1:246
	v_add_u32_e32 v3, 0x1c00, v102
	s_waitcnt vmcnt(2)
	ds_write2_b32 v3, v8, v9 offset0:56 offset1:122
	s_waitcnt vmcnt(0)
	ds_write2_b32 v3, v10, v2 offset0:188 offset1:254
	s_waitcnt lgkmcnt(0)
	ds_read2_b32 v[6:7], v104 offset0:33 offset1:41
	ds_read2_b32 v[8:9], v104 offset1:8
	ds_read2_b32 v[10:11], v104 offset0:66 offset1:74
	ds_read2_b32 v[12:13], v104 offset0:99 offset1:107
	ds_read2_b32 v[14:15], v104 offset0:132 offset1:140
	ds_read2_b32 v[16:17], v104 offset0:165 offset1:173
	ds_read2_b32 v[18:19], v104 offset0:198 offset1:206
	ds_read2_b32 v[20:21], v104 offset0:231 offset1:239
	s_mov_b32 s1, s7
	s_waitcnt lgkmcnt(6)
	v_cvt_pk_bf16_f32 v2, v8, v6
	v_or_b32_e32 v6, s2, v103
	v_lshl_add_u64 v[22:23], s[0:1], 1, v[86:87]
	v_lshlrev_b32_e32 v68, 11, v6
	s_waitcnt lgkmcnt(4)
	v_cvt_pk_bf16_f32 v3, v10, v12
	s_waitcnt lgkmcnt(2)
	v_cvt_pk_bf16_f32 v4, v14, v16
	s_waitcnt lgkmcnt(0)
	v_cvt_pk_bf16_f32 v5, v18, v20
	v_lshl_add_u64 v[24:25], v[22:23], 0, v[68:69]
	global_store_dwordx4 v[24:25], v[2:5], off
	v_or_b32_e32 v6, s2, v105
	v_lshlrev_b32_e32 v68, 11, v6
	v_cvt_pk_bf16_f32 v2, v9, v7
	v_cvt_pk_bf16_f32 v3, v11, v13
	v_cvt_pk_bf16_f32 v4, v15, v17
	v_cvt_pk_bf16_f32 v5, v19, v21
	ds_read2_b32 v[8:9], v104 offset0:49 offset1:57
	ds_read2_b32 v[10:11], v104 offset0:16 offset1:24
	ds_read2_b32 v[12:13], v104 offset0:82 offset1:90
	ds_read2_b32 v[14:15], v104 offset0:115 offset1:123
	ds_read2_b32 v[16:17], v104 offset0:148 offset1:156
	ds_read2_b32 v[18:19], v104 offset0:181 offset1:189
	ds_read2_b32 v[20:21], v104 offset0:214 offset1:222
	ds_read2_b32 v[24:25], v104 offset0:247 offset1:255
	v_lshl_add_u64 v[6:7], v[22:23], 0, v[68:69]
	global_store_dwordx4 v[6:7], v[2:5], off
	v_or_b32_e32 v6, s2, v106
	v_lshlrev_b32_e32 v68, 11, v6
	s_waitcnt lgkmcnt(6)
	v_cvt_pk_bf16_f32 v2, v10, v8
	s_waitcnt lgkmcnt(4)
	v_cvt_pk_bf16_f32 v3, v12, v14
	s_waitcnt lgkmcnt(2)
	v_cvt_pk_bf16_f32 v4, v16, v18
	s_waitcnt lgkmcnt(0)
	v_cvt_pk_bf16_f32 v5, v20, v24
	v_lshl_add_u64 v[6:7], v[22:23], 0, v[68:69]
	global_store_dwordx4 v[6:7], v[2:5], off
	v_or_b32_e32 v6, s2, v107
	v_lshlrev_b32_e32 v68, 11, v6
	v_cvt_pk_bf16_f32 v2, v11, v9
	v_cvt_pk_bf16_f32 v3, v13, v15
	v_cvt_pk_bf16_f32 v4, v17, v19
	v_cvt_pk_bf16_f32 v5, v21, v25
	v_lshl_add_u64 v[6:7], v[22:23], 0, v[68:69]
	global_store_dwordx4 v[6:7], v[2:5], off
	s_waitcnt lgkmcnt(0)

; DI void transpose_item(const GAS float* W, int K, int N, GAS bf16* WT, int vrow0, int scol0, int k0, LAS float* scr, int lane) {
;     ...
;     for (int i = 0; i < 32; ++i) wv[i] = __builtin_nontemporal_load(W + (size_t)(k0 + 2 * i + (lane >> 5)) * N + scol0 + (lane & 31));
; DI void phase_prep(const Ctx& C) {
;     ...
;             if (it < T_W2) { const int mat = it / (44 * 32), r = it % (44 * 32), kb = r / 32, nb = r % 32;
;                 transpose_item(INP(I_FWOUT) + (size_t)mat * DFF * 1024, DFF, 1024, WSP(bf16, WS_W2T) + (size_t)mat * W2T_SZ, 32 * nb, 32 * nb, 64 * kb, scr, lane); continue; }
.LBB0_54:
	s_andn2_b64 vcc, exec, s[0:1]
	s_cbranch_vccnz .LBB0_56
	s_add_i32 s0, s26, 0xcf80
	s_and_b32 s1, s0, 0xffff
	s_mul_i32 s1, s1, 0xba2f
	s_lshr_b32 s1, s1, 26
	s_mul_i32 s2, s1, 0x580
	s_sub_i32 s0, s0, s2
	s_and_b32 s3, s0, 0xffff
	s_mul_i32 s0, s1, 0xb00000
	s_add_u32 s4, s10, s0
	s_addc_u32 s5, s11, 0
	s_mul_i32 s1, s1, 0x580000
	s_add_u32 s1, s29, s1
	s_addc_u32 s2, s30, 0
	s_lshl_b32 s0, s3, 5
	s_and_b32 s0, s0, 0x3e0
	s_lshl_b32 s3, s3, 1
	s_and_b32 s3, s3, 0xfc0
	s_lshl_b32 s6, s0, 2
	s_add_u32 s4, s4, s6
	v_or_b32_e32 v4, s3, v101
	s_addc_u32 s5, s5, 0
	v_lshlrev_b32_e32 v68, 2, v70
	v_lshl_add_u64 v[2:3], s[4:5], 0, v[68:69]
	v_lshlrev_b32_e32 v68, 12, v4
	v_lshl_add_u64 v[2:3], v[2:3], 0, v[68:69]
	s_movk_i32 s4, 0x2000
	v_add_co_u32_e32 v4, vcc, s4, v2
	s_mov_b32 s4, 0x8000
	s_nop 0
	v_addc_co_u32_e32 v5, vcc, 0, v3, vcc
	v_add_co_u32_e32 v6, vcc, s81, v2
	s_lshl_b32 s3, s3, 1
	s_nop 0
	v_addc_co_u32_e32 v7, vcc, 0, v3, vcc
	v_add_co_u32_e32 v8, vcc, s97, v2
	v_lshlrev_b32_e32 v68, 1, v72
	s_nop 0
	v_addc_co_u32_e32 v9, vcc, 0, v3, vcc
	v_add_co_u32_e32 v10, vcc, s4, v2
	s_mov_b32 s4, 0xa000
	s_nop 0
	v_addc_co_u32_e32 v11, vcc, 0, v3, vcc
	v_add_co_u32_e32 v12, vcc, s4, v2
	s_mov_b32 s4, 0xe000
	s_nop 0
	v_addc_co_u32_e32 v13, vcc, 0, v3, vcc
	v_add_co_u32_e32 v14, vcc, s65, v2
	s_nop 1
	v_addc_co_u32_e32 v15, vcc, 0, v3, vcc
	v_add_co_u32_e32 v16, vcc, s4, v2
	s_mov_b32 s4, 0x10000
	s_nop 0
	v_addc_co_u32_e32 v17, vcc, 0, v3, vcc
	global_load_dword v20, v[2:3], off
	global_load_dword v21, v[4:5], off
	global_load_dword v22, v[6:7], off
	global_load_dword v23, v[8:9], off
	global_load_dword v24, v[10:11], off
	global_load_dword v25, v[12:13], off
	global_load_dword v26, v[14:15], off
	global_load_dword v27, v[16:17], off
	v_add_co_u32_e32 v4, vcc, s4, v2
	s_mov_b32 s4, 0x14000
	s_nop 0
	v_addc_co_u32_e32 v5, vcc, 0, v3, vcc
	v_add_co_u32_e32 v6, vcc, s83, v2
	s_nop 1
	v_addc_co_u32_e32 v7, vcc, 0, v3, vcc
	v_add_co_u32_e32 v8, vcc, s4, v2
	s_mov_b32 s4, 0x1a000
	s_nop 0
	v_addc_co_u32_e32 v9, vcc, 0, v3, vcc
	v_add_co_u32_e32 v10, vcc, s84, v2
	s_nop 1
	v_addc_co_u32_e32 v11, vcc, 0, v3, vcc
	v_add_co_u32_e32 v12, vcc, s66, v2
	s_nop 1
	v_addc_co_u32_e32 v13, vcc, 0, v3, vcc
	v_add_co_u32_e32 v14, vcc, s4, v2
	s_mov_b32 s4, 0x1c000
	s_nop 0
	v_addc_co_u32_e32 v15, vcc, 0, v3, vcc
	v_add_co_u32_e32 v16, vcc, s4, v2
	s_mov_b32 s4, 0x20000
	s_nop 0
	v_addc_co_u32_e32 v17, vcc, 0, v3, vcc
	v_add_co_u32_e32 v18, vcc, s67, v2
	s_nop 1
	v_addc_co_u32_e32 v19, vcc, 0, v3, vcc
	global_load_dword v28, v[4:5], off
	global_load_dword v29, v[6:7], off
	global_load_dword v30, v[8:9], off
	global_load_dword v31, v[10:11], off
	global_load_dword v32, v[12:13], off
	global_load_dword v33, v[14:15], off
	global_load_dword v34, v[16:17], off
	global_load_dword v35, v[18:19], off
	v_add_co_u32_e32 v4, vcc, s4, v2
	s_mov_b32 s4, 0x22000
	s_nop 0
	v_addc_co_u32_e32 v5, vcc, 0, v3, vcc
	v_add_co_u32_e32 v6, vcc, s4, v2
	s_mov_b32 s4, 0x26000
	s_nop 0
	v_addc_co_u32_e32 v7, vcc, 0, v3, vcc
	v_add_co_u32_e32 v8, vcc, s86, v2
	s_nop 1
	v_addc_co_u32_e32 v9, vcc, 0, v3, vcc
	v_add_co_u32_e32 v10, vcc, s4, v2
	s_mov_b32 s4, 0x2e000
	s_nop 0
	v_addc_co_u32_e32 v11, vcc, 0, v3, vcc
	v_add_co_u32_e32 v12, vcc, s87, v2
	s_nop 1
	v_addc_co_u32_e32 v13, vcc, 0, v3, vcc
	v_add_co_u32_e32 v14, vcc, s75, v2
	s_nop 1
	v_addc_co_u32_e32 v15, vcc, 0, v3, vcc
	v_add_co_u32_e32 v16, vcc, s79, v2
	s_nop 1
	v_addc_co_u32_e32 v17, vcc, 0, v3, vcc
	v_add_co_u32_e32 v18, vcc, s4, v2
	s_mov_b32 s4, 0x32000
	s_nop 0
	v_addc_co_u32_e32 v19, vcc, 0, v3, vcc
	global_load_dword v36, v[4:5], off
	global_load_dword v37, v[6:7], off
	global_load_dword v38, v[8:9], off
	global_load_dword v39, v[10:11], off
	global_load_dword v40, v[12:13], off
	global_load_dword v41, v[14:15], off
	global_load_dword v42, v[16:17], off
	s_nop 0
	global_load_dword v18, v[18:19], off
	v_add_co_u32_e32 v4, vcc, s76, v2
	s_nop 1
	v_addc_co_u32_e32 v5, vcc, 0, v3, vcc
	v_add_co_u32_e32 v6, vcc, s4, v2
	s_mov_b32 s4, 0x34000
	s_nop 0
	v_addc_co_u32_e32 v7, vcc, 0, v3, vcc
	v_add_co_u32_e32 v8, vcc, s4, v2
	s_mov_b32 s4, 0x38000
	s_nop 0
	v_addc_co_u32_e32 v9, vcc, 0, v3, vcc
	v_add_co_u32_e32 v10, vcc, s89, v2
	s_nop 1
	v_addc_co_u32_e32 v11, vcc, 0, v3, vcc
	v_add_co_u32_e32 v12, vcc, s4, v2
	s_mov_b32 s4, 0x3e000
	s_nop 0
	v_addc_co_u32_e32 v13, vcc, 0, v3, vcc
	v_add_co_u32_e32 v14, vcc, s90, v2
	s_nop 1
	v_addc_co_u32_e32 v15, vcc, 0, v3, vcc
	v_add_co_u32_e32 v16, vcc, s77, v2
	s_nop 1
	v_addc_co_u32_e32 v17, vcc, 0, v3, vcc
	v_add_co_u32_e32 v2, vcc, s4, v2
	s_add_u32 s4, s1, s3
	s_nop 0
	v_addc_co_u32_e32 v3, vcc, 0, v3, vcc
	global_load_dword v4, v[4:5], off
	s_nop 0
	global_load_dword v5, v[6:7], off
	s_nop 0
	global_load_dword v6, v[8:9], off
	global_load_dword v7, v[10:11], off
	s_nop 0
	global_load_dword v8, v[12:13], off
	global_load_dword v9, v[14:15], off
	global_load_dword v10, v[16:17], off
	s_nop 0
	global_load_dword v2, v[2:3], off
	v_add_u32_e32 v3, 0x400, v102
	s_waitcnt vmcnt(30)
; #define LAS __attribute__((address_space(3)))
; #define GAS __attribute__((address_space(1)))
; DI unsigned pk2(float lo, float hi) { f32x2_t v = {lo, hi}; bf16x2_t b = __builtin_convertvector(v, bf16x2_t); return __builtin_bit_cast(unsigned, b); }
; DI void transpose_item(const GAS float* W, int K, int N, GAS bf16* WT, int vrow0, int scol0, int k0, LAS float* scr, int lane) {
;     ...
;     for (int i = 0; i < 32; ++i) scr[(2 * i + (lane >> 5)) * 33 + (lane & 31)] = wv[i];
;     asm volatile("s_waitcnt lgkmcnt(0)" ::: "memory");
;     const int c = lane & 7;
; #pragma unroll
;     for (int j = 0; j < 4; ++j) { const int n = (lane >> 3) + 8 * j; const LAS float* s = scr + (8 * c) * 33 + n;
;         u32x4 o; o.x = pk2(s[0 * 33], s[1 * 33]); o.y = pk2(s[2 * 33], s[3 * 33]); o.z = pk2(s[4 * 33], s[5 * 33]); o.w = pk2(s[6 * 33], s[7 * 33]);
;         *(GAS u32x4*)(WT + (size_t)(vrow0 + n) * K + k0 + 8 * c) = o; }
	ds_write2_b32 v102, v20, v21 offset1:66
	s_waitcnt vmcnt(28)
	ds_write2_b32 v102, v22, v23 offset0:132 offset1:198
	s_waitcnt vmcnt(26)
	ds_write2_b32 v3, v24, v25 offset0:8 offset1:74
	s_waitcnt vmcnt(24)
	ds_write2_b32 v3, v26, v27 offset0:140 offset1:206
	v_add_u32_e32 v3, 0x800, v102
	s_waitcnt vmcnt(22)
	ds_write2_b32 v3, v28, v29 offset0:16 offset1:82
	s_waitcnt vmcnt(20)
	ds_write2_b32 v3, v30, v31 offset0:148 offset1:214
	v_add_u32_e32 v3, 0xc00, v102
	s_waitcnt vmcnt(18)
	ds_write2_b32 v3, v32, v33 offset0:24 offset1:90
	s_waitcnt vmcnt(16)
	ds_write2_b32 v3, v34, v35 offset0:156 offset1:222
	v_add_u32_e32 v3, 0x1000, v102
	s_waitcnt vmcnt(14)
	ds_write2_b32 v3, v36, v37 offset0:32 offset1:98
	s_waitcnt vmcnt(12)
	ds_write2_b32 v3, v38, v39 offset0:164 offset1:230
	v_add_u32_e32 v3, 0x1400, v102
	s_waitcnt vmcnt(10)
	ds_write2_b32 v3, v40, v41 offset0:40 offset1:106
	s_waitcnt vmcnt(8)
	ds_write2_b32 v3, v42, v18 offset0:172 offset1:238
	v_add_u32_e32 v3, 0x1800, v102
	s_waitcnt vmcnt(6)
	ds_write2_b32 v3, v4, v5 offset0:48 offset1:114
	s_waitcnt vmcnt(4)
	ds_write2_b32 v3, v6, v7 offset0:180 offset1:246
	v_add_u32_e32 v3, 0x1c00, v102
	s_waitcnt vmcnt(2)
	ds_write2_b32 v3, v8, v9 offset0:56 offset1:122
	s_waitcnt vmcnt(0)
	ds_write2_b32 v3, v10, v2 offset0:188 offset1:254
	s_waitcnt lgkmcnt(0)
	ds_read2_b32 v[6:7], v104 offset0:33 offset1:41
	ds_read2_b32 v[8:9], v104 offset1:8
	ds_read2_b32 v[10:11], v104 offset0:66 offset1:74
	ds_read2_b32 v[12:13], v104 offset0:99 offset1:107
	ds_read2_b32 v[14:15], v104 offset0:132 offset1:140
	ds_read2_b32 v[16:17], v104 offset0:165 offset1:173
	ds_read2_b32 v[18:19], v104 offset0:198 offset1:206
	ds_read2_b32 v[20:21], v104 offset0:231 offset1:239
	s_addc_u32 s5, s2, 0
	s_waitcnt lgkmcnt(6)
	v_cvt_pk_bf16_f32 v2, v8, v6
	v_or_b32_e32 v6, s0, v103
	v_lshl_add_u64 v[22:23], s[4:5], 0, v[68:69]
	v_mul_u32_u24_e32 v68, 0x1600, v6
	s_waitcnt lgkmcnt(4)
	v_cvt_pk_bf16_f32 v3, v10, v12
	s_waitcnt lgkmcnt(2)
	v_cvt_pk_bf16_f32 v4, v14, v16
	s_waitcnt lgkmcnt(0)
	v_cvt_pk_bf16_f32 v5, v18, v20
	v_lshl_add_u64 v[24:25], v[22:23], 0, v[68:69]
	global_store_dwordx4 v[24:25], v[2:5], off
	v_or_b32_e32 v6, s0, v105
	v_mul_u32_u24_e32 v68, 0x1600, v6
	v_cvt_pk_bf16_f32 v2, v9, v7
	v_cvt_pk_bf16_f32 v3, v11, v13
	v_cvt_pk_bf16_f32 v4, v15, v17
	v_cvt_pk_bf16_f32 v5, v19, v21
	ds_read2_b32 v[8:9], v104 offset0:16 offset1:24
	ds_read2_b32 v[10:11], v104 offset0:49 offset1:57
	ds_read2_b32 v[12:13], v104 offset0:82 offset1:90
	ds_read2_b32 v[14:15], v104 offset0:115 offset1:123
	ds_read2_b32 v[16:17], v104 offset0:148 offset1:156
	ds_read2_b32 v[18:19], v104 offset0:181 offset1:189
	ds_read2_b32 v[20:21], v104 offset0:214 offset1:222
	ds_read2_b32 v[24:25], v104 offset0:247 offset1:255
	v_lshl_add_u64 v[6:7], v[22:23], 0, v[68:69]
	global_store_dwordx4 v[6:7], v[2:5], off
	v_or_b32_e32 v6, s0, v106
	v_mul_u32_u24_e32 v68, 0x1600, v6
	s_waitcnt lgkmcnt(6)
	v_cvt_pk_bf16_f32 v2, v8, v10
	s_waitcnt lgkmcnt(4)
	v_cvt_pk_bf16_f32 v3, v12, v14
	s_waitcnt lgkmcnt(2)
	v_cvt_pk_bf16_f32 v4, v16, v18
	s_waitcnt lgkmcnt(0)
	v_cvt_pk_bf16_f32 v5, v20, v24
	v_lshl_add_u64 v[6:7], v[22:23], 0, v[68:69]
	global_store_dwordx4 v[6:7], v[2:5], off
	v_or_b32_e32 v6, s0, v107
	v_mul_u32_u24_e32 v68, 0x1600, v6
	v_cvt_pk_bf16_f32 v2, v9, v11
	v_cvt_pk_bf16_f32 v3, v13, v15
	v_cvt_pk_bf16_f32 v4, v17, v19
	v_cvt_pk_bf16_f32 v5, v21, v25
	v_lshl_add_u64 v[6:7], v[22:23], 0, v[68:69]
	global_store_dwordx4 v[6:7], v[2:5], off
	s_waitcnt lgkmcnt(0)

; #define LAS __attribute__((address_space(3)))
; #define GAS __attribute__((address_space(1)))
; DI int glu_map128(int v, int half_off) { return ((v & 255) >= 128 ? half_off : 0) + 128 * (v >> 8) + (v & 127); }
; DI void transpose_item(const GAS float* W, int K, int N, GAS bf16* WT, int vrow0, int scol0, int k0, LAS float* scr, int lane) {
;     float wv[32];
; #pragma unroll
;     for (int i = 0; i < 32; ++i) wv[i] = __builtin_nontemporal_load(W + (size_t)(k0 + 2 * i + (lane >> 5)) * N + scol0 + (lane & 31));
; #pragma unroll
;     for (int i = 0; i < 32; ++i) scr[(2 * i + (lane >> 5)) * 33 + (lane & 31)] = wv[i];
; DI void phase_prep(const Ctx& C) {
;     ...
;             if (it < T_W1) { const int mat = it / (16 * 176), r = it % (16 * 176), kb = r / 176, nb = r % 176;
;                 transpose_item(INP(I_FWIN) + (size_t)mat * 1024 * 5632, 1024, 5632, WSP(bf16, WS_W1T) + (size_t)mat * W1T_SZ, 32 * nb, glu_map128(32 * nb, DFF), 64 * kb, scr, lane); continue; }
.LBB0_57:
	s_andn2_b64 vcc, exec, s[0:1]
	s_cbranch_vccnz .LBB0_59
	s_add_i32 s0, s26, 0xfb80
	s_and_b32 s1, s0, 0xffff
	s_mul_i32 s1, s1, 0xba2f
	s_lshr_b32 s2, s1, 27
	s_mul_i32 s1, s2, 0xb00
	s_sub_i32 s0, s0, s1
	s_and_b32 s1, s0, 0xffff
	s_mul_i32 s1, s1, 0xba2f
	s_lshr_b32 s1, s1, 23
	s_mul_i32 s3, s1, 0xb0
	s_sub_i32 s4, s0, s3
	s_mul_i32 s0, s2, 0x1600000
	s_add_u32 s5, s8, s0
	s_addc_u32 s6, s9, 0
	s_mul_i32 s2, s2, 0xb00000
	s_add_u32 s2, s31, s2
	s_addc_u32 s3, s62, 0
	s_lshl_b32 s33, s4, 5
	s_bfe_i32 s36, s4, 0x10002
	s_lshl_b32 s4, s4, 4
	s_and_b32 s0, s33, 0xffe0
	s_and_b32 s4, s4, 0xf80
	s_and_b32 s33, s33, 0x60
	s_and_b32 s36, s36, 0xb00
	s_or_b32 s4, s4, s33
	s_add_i32 s4, s4, s36
	s_lshl_b32 s4, s4, 2
	s_add_u32 s4, s5, s4
	v_lshl_or_b32 v4, s1, 6, v101
	s_addc_u32 s5, s6, 0
	v_lshlrev_b32_e32 v68, 2, v70
	v_lshl_add_u64 v[2:3], s[4:5], 0, v[68:69]
	v_mul_u32_u24_e32 v68, 0x5800, v4
	v_lshl_add_u64 v[2:3], v[2:3], 0, v[68:69]
	s_mov_b32 s4, 0xb000
	v_add_co_u32_e32 v4, vcc, s4, v2
	s_mov_b32 s4, 0x37000
	s_nop 0
	v_addc_co_u32_e32 v5, vcc, 0, v3, vcc
	v_add_co_u32_e32 v6, vcc, s84, v2
	s_lshl_b32 s1, s1, 7
	s_nop 0
	v_addc_co_u32_e32 v7, vcc, 0, v3, vcc
	v_add_co_u32_e32 v8, vcc, s74, v2
	s_add_u32 s2, s2, s1
	s_nop 0
	v_addc_co_u32_e32 v9, vcc, 0, v3, vcc
	v_add_co_u32_e32 v10, vcc, s79, v2
	s_addc_u32 s3, s3, 0
	s_nop 0
	v_addc_co_u32_e32 v11, vcc, 0, v3, vcc
	v_add_co_u32_e32 v12, vcc, s4, v2
	s_mov_b32 s4, 0x4d000
	s_nop 0
	v_addc_co_u32_e32 v13, vcc, 0, v3, vcc
	v_add_co_u32_e32 v14, vcc, s78, v2
	v_lshlrev_b32_e32 v68, 1, v72
	s_nop 0
	v_addc_co_u32_e32 v15, vcc, 0, v3, vcc
	v_add_co_u32_e32 v16, vcc, s4, v2
	s_mov_b32 s4, 0x58000
	s_nop 0
	v_addc_co_u32_e32 v17, vcc, 0, v3, vcc
	global_load_dword v20, v[2:3], off
	global_load_dword v21, v[4:5], off
	global_load_dword v22, v[6:7], off
	global_load_dword v23, v[8:9], off
	global_load_dword v24, v[10:11], off
	global_load_dword v25, v[12:13], off
	global_load_dword v26, v[14:15], off
	global_load_dword v27, v[16:17], off
	v_add_co_u32_e32 v4, vcc, s4, v2
	s_mov_b32 s4, 0x6e000
	s_nop 0
	v_addc_co_u32_e32 v5, vcc, 0, v3, vcc
	v_add_co_u32_e32 v6, vcc, s95, v2
	s_nop 1
	v_addc_co_u32_e32 v7, vcc, 0, v3, vcc
	v_add_co_u32_e32 v8, vcc, s4, v2
	s_mov_b32 s4, 0x84000
	s_nop 0
	v_addc_co_u32_e32 v9, vcc, 0, v3, vcc
	v_add_co_u32_e32 v10, vcc, s96, v2
	s_nop 1
	v_addc_co_u32_e32 v11, vcc, 0, v3, vcc
	v_add_co_u32_e32 v12, vcc, s4, v2
	s_mov_b32 s4, 0x8f000
	s_nop 0
	v_addc_co_u32_e32 v13, vcc, 0, v3, vcc
	v_add_co_u32_e32 v14, vcc, s4, v2
	s_mov_b32 s4, 0x9a000
	s_nop 0
	v_addc_co_u32_e32 v15, vcc, 0, v3, vcc
	v_add_co_u32_e32 v16, vcc, s4, v2
	s_mov_b32 s4, 0xa5000
	s_nop 0
	v_addc_co_u32_e32 v17, vcc, 0, v3, vcc
	v_add_co_u32_e32 v18, vcc, s4, v2
	s_mov_b32 s4, 0xb0000
	s_nop 0
	v_addc_co_u32_e32 v19, vcc, 0, v3, vcc
	global_load_dword v28, v[4:5], off
	global_load_dword v29, v[6:7], off
	global_load_dword v30, v[8:9], off
	global_load_dword v31, v[10:11], off
	global_load_dword v32, v[12:13], off
	global_load_dword v33, v[14:15], off
	global_load_dword v34, v[16:17], off
	global_load_dword v35, v[18:19], off
	v_add_co_u32_e32 v4, vcc, s4, v2
	s_mov_b32 s4, 0xbb000
	s_nop 0
	v_addc_co_u32_e32 v5, vcc, 0, v3, vcc
	v_add_co_u32_e32 v6, vcc, s4, v2
	s_mov_b32 s4, 0xc6000
	s_nop 0
	v_addc_co_u32_e32 v7, vcc, 0, v3, vcc
	v_add_co_u32_e32 v8, vcc, s4, v2
	s_mov_b32 s4, 0xd1000
	s_nop 0
	v_addc_co_u32_e32 v9, vcc, 0, v3, vcc
	v_add_co_u32_e32 v10, vcc, s4, v2
	s_mov_b32 s4, 0xdc000
	s_nop 0
	v_addc_co_u32_e32 v11, vcc, 0, v3, vcc
	v_add_co_u32_e32 v12, vcc, s4, v2
	s_mov_b32 s4, 0xe7000
	s_nop 0
	v_addc_co_u32_e32 v13, vcc, 0, v3, vcc
	v_add_co_u32_e32 v14, vcc, s4, v2
	s_mov_b32 s4, 0xf2000
	s_nop 0
	v_addc_co_u32_e32 v15, vcc, 0, v3, vcc
	v_add_co_u32_e32 v16, vcc, s4, v2
	s_mov_b32 s4, 0xfd000
	s_nop 0
	v_addc_co_u32_e32 v17, vcc, 0, v3, vcc
	v_add_co_u32_e32 v18, vcc, s4, v2
	s_mov_b32 s4, 0x108000
	s_nop 0
	v_addc_co_u32_e32 v19, vcc, 0, v3, vcc
	global_load_dword v36, v[4:5], off
	global_load_dword v37, v[6:7], off
	global_load_dword v38, v[8:9], off
	global_load_dword v39, v[10:11], off
	global_load_dword v40, v[12:13], off
	global_load_dword v41, v[14:15], off
	global_load_dword v42, v[16:17], off
	s_nop 0
	global_load_dword v18, v[18:19], off
	v_add_co_u32_e32 v4, vcc, s4, v2
	s_mov_b32 s4, 0x113000
	s_nop 0
	v_addc_co_u32_e32 v5, vcc, 0, v3, vcc
	v_add_co_u32_e32 v6, vcc, s4, v2
	s_mov_b32 s4, 0x11e000
	s_nop 0
	v_addc_co_u32_e32 v7, vcc, 0, v3, vcc
	v_add_co_u32_e32 v8, vcc, s4, v2
	s_mov_b32 s4, 0x129000
	s_nop 0
	v_addc_co_u32_e32 v9, vcc, 0, v3, vcc
	v_add_co_u32_e32 v10, vcc, s4, v2
	s_mov_b32 s4, 0x134000
	s_nop 0
	v_addc_co_u32_e32 v11, vcc, 0, v3, vcc
	v_add_co_u32_e32 v12, vcc, s4, v2
	s_mov_b32 s4, 0x13f000
	s_nop 0
	v_addc_co_u32_e32 v13, vcc, 0, v3, vcc
	v_add_co_u32_e32 v14, vcc, s4, v2
	s_mov_b32 s4, 0x14a000
	s_nop 0
	v_addc_co_u32_e32 v15, vcc, 0, v3, vcc
	v_add_co_u32_e32 v16, vcc, s4, v2
	s_mov_b32 s4, 0x155000
	s_nop 0
	v_addc_co_u32_e32 v17, vcc, 0, v3, vcc
	v_add_co_u32_e32 v2, vcc, s4, v2
	s_nop 1
	v_addc_co_u32_e32 v3, vcc, 0, v3, vcc
	global_load_dword v4, v[4:5], off
	s_nop 0
	global_load_dword v5, v[6:7], off
	s_nop 0
	global_load_dword v6, v[8:9], off
	global_load_dword v7, v[10:11], off
	s_nop 0
	global_load_dword v8, v[12:13], off
	global_load_dword v9, v[14:15], off
	global_load_dword v10, v[16:17], off
	s_nop 0
	global_load_dword v2, v[2:3], off
	v_add_u32_e32 v3, 0x400, v102
	s_waitcnt vmcnt(30)
; #define LAS __attribute__((address_space(3)))
; #define GAS __attribute__((address_space(1)))
; DI unsigned pk2(float lo, float hi) { f32x2_t v = {lo, hi}; bf16x2_t b = __builtin_convertvector(v, bf16x2_t); return __builtin_bit_cast(unsigned, b); }
; DI void transpose_item(const GAS float* W, int K, int N, GAS bf16* WT, int vrow0, int scol0, int k0, LAS float* scr, int lane) {
;     ...
;     for (int i = 0; i < 32; ++i) scr[(2 * i + (lane >> 5)) * 33 + (lane & 31)] = wv[i];
;     asm volatile("s_waitcnt lgkmcnt(0)" ::: "memory");
;     const int c = lane & 7;
; #pragma unroll
;     for (int j = 0; j < 4; ++j) { const int n = (lane >> 3) + 8 * j; const LAS float* s = scr + (8 * c) * 33 + n;
;         u32x4 o; o.x = pk2(s[0 * 33], s[1 * 33]); o.y = pk2(s[2 * 33], s[3 * 33]); o.z = pk2(s[4 * 33], s[5 * 33]); o.w = pk2(s[6 * 33], s[7 * 33]);
;         *(GAS u32x4*)(WT + (size_t)(vrow0 + n) * K + k0 + 8 * c) = o; }
;     asm volatile("s_waitcnt lgkmcnt(0)" ::: "memory");
	ds_write2_b32 v102, v20, v21 offset1:66
	s_waitcnt vmcnt(28)
	ds_write2_b32 v102, v22, v23 offset0:132 offset1:198
	s_waitcnt vmcnt(26)
	ds_write2_b32 v3, v24, v25 offset0:8 offset1:74
	s_waitcnt vmcnt(24)
	ds_write2_b32 v3, v26, v27 offset0:140 offset1:206
	v_add_u32_e32 v3, 0x800, v102
	s_waitcnt vmcnt(22)
	ds_write2_b32 v3, v28, v29 offset0:16 offset1:82
	s_waitcnt vmcnt(20)
	ds_write2_b32 v3, v30, v31 offset0:148 offset1:214
	v_add_u32_e32 v3, 0xc00, v102
	s_waitcnt vmcnt(18)
	ds_write2_b32 v3, v32, v33 offset0:24 offset1:90
	s_waitcnt vmcnt(16)
	ds_write2_b32 v3, v34, v35 offset0:156 offset1:222
	v_add_u32_e32 v3, 0x1000, v102
	s_waitcnt vmcnt(14)
	ds_write2_b32 v3, v36, v37 offset0:32 offset1:98
	s_waitcnt vmcnt(12)
	ds_write2_b32 v3, v38, v39 offset0:164 offset1:230
	v_add_u32_e32 v3, 0x1400, v102
	s_waitcnt vmcnt(10)
	ds_write2_b32 v3, v40, v41 offset0:40 offset1:106
	s_waitcnt vmcnt(8)
	ds_write2_b32 v3, v42, v18 offset0:172 offset1:238
	v_add_u32_e32 v3, 0x1800, v102
	s_waitcnt vmcnt(6)
	ds_write2_b32 v3, v4, v5 offset0:48 offset1:114
	s_waitcnt vmcnt(4)
	ds_write2_b32 v3, v6, v7 offset0:180 offset1:246
	v_add_u32_e32 v3, 0x1c00, v102
	s_waitcnt vmcnt(2)
	ds_write2_b32 v3, v8, v9 offset0:56 offset1:122
	s_waitcnt vmcnt(0)
	ds_write2_b32 v3, v10, v2 offset0:188 offset1:254
	s_waitcnt lgkmcnt(0)
	ds_read2_b32 v[6:7], v104 offset0:33 offset1:41
	ds_read2_b32 v[8:9], v104 offset1:8
	ds_read2_b32 v[10:11], v104 offset0:66 offset1:74
	ds_read2_b32 v[12:13], v104 offset0:99 offset1:107
	ds_read2_b32 v[14:15], v104 offset0:132 offset1:140
	ds_read2_b32 v[16:17], v104 offset0:165 offset1:173
	ds_read2_b32 v[18:19], v104 offset0:198 offset1:206
	ds_read2_b32 v[20:21], v104 offset0:231 offset1:239
	s_waitcnt lgkmcnt(6)
	v_cvt_pk_bf16_f32 v2, v8, v6
	v_or_b32_e32 v6, s0, v103
	v_lshl_add_u64 v[22:23], s[2:3], 0, v[68:69]
	v_lshlrev_b32_e32 v68, 11, v6
	s_waitcnt lgkmcnt(4)
	v_cvt_pk_bf16_f32 v3, v10, v12
	s_waitcnt lgkmcnt(2)
	v_cvt_pk_bf16_f32 v4, v14, v16
	s_waitcnt lgkmcnt(0)
	v_cvt_pk_bf16_f32 v5, v18, v20
	v_lshl_add_u64 v[24:25], v[22:23], 0, v[68:69]
	global_store_dwordx4 v[24:25], v[2:5], off
	v_or_b32_e32 v6, s0, v105
	v_lshlrev_b32_e32 v68, 11, v6
	v_cvt_pk_bf16_f32 v2, v9, v7
	v_cvt_pk_bf16_f32 v3, v11, v13
	v_cvt_pk_bf16_f32 v4, v15, v17
	v_cvt_pk_bf16_f32 v5, v19, v21
	ds_read2_b32 v[8:9], v104 offset0:49 offset1:57
	ds_read2_b32 v[10:11], v104 offset0:16 offset1:24
	ds_read2_b32 v[12:13], v104 offset0:82 offset1:90
	ds_read2_b32 v[14:15], v104 offset0:115 offset1:123
	ds_read2_b32 v[16:17], v104 offset0:148 offset1:156
	ds_read2_b32 v[18:19], v104 offset0:181 offset1:189
	ds_read2_b32 v[20:21], v104 offset0:214 offset1:222
	ds_read2_b32 v[24:25], v104 offset0:247 offset1:255
	v_lshl_add_u64 v[6:7], v[22:23], 0, v[68:69]
	global_store_dwordx4 v[6:7], v[2:5], off
	v_or_b32_e32 v6, s0, v106
	v_lshlrev_b32_e32 v68, 11, v6
	s_waitcnt lgkmcnt(6)
	v_cvt_pk_bf16_f32 v2, v10, v8
	s_waitcnt lgkmcnt(4)
	v_cvt_pk_bf16_f32 v3, v12, v14
	s_waitcnt lgkmcnt(2)
	v_cvt_pk_bf16_f32 v4, v16, v18
	s_waitcnt lgkmcnt(0)
	v_cvt_pk_bf16_f32 v5, v20, v24
	v_lshl_add_u64 v[6:7], v[22:23], 0, v[68:69]
	global_store_dwordx4 v[6:7], v[2:5], off
	v_or_b32_e32 v6, s0, v107
	v_lshlrev_b32_e32 v68, 11, v6
	v_cvt_pk_bf16_f32 v2, v11, v9
	v_cvt_pk_bf16_f32 v3, v13, v15
	v_cvt_pk_bf16_f32 v4, v17, v19
	v_cvt_pk_bf16_f32 v5, v21, v25
	v_lshl_add_u64 v[6:7], v[22:23], 0, v[68:69]
	global_store_dwordx4 v[6:7], v[2:5], off
	s_waitcnt lgkmcnt(0)
